# stack: attention waits + stray prologue vmcnt removed (P3/P5/P6) + P1 gain-table deferred + B fragment batching + A K-frag hoist + S-init copies via SrcC
# speedup vs baseline: 1.0144x; 1.0055x over previous
;     __host__ __device__ void init(int M, int N, int M2, int N2, int G_, int c_) { S1.init(M, N, G_, c_); nM2 = M2 / BM; nN2 = N2 / BM; }
;     __host__ __device__ void init(int M, int N, int nrep_, int G_, int c_) { S1.init(M, N, G_, c_); nrep = nrep_; }
; __device__ __forceinline__ int tid_fresh(int wave) { return wave * 64 + lane_id_fresh(); }
; #define LAS __attribute__((address_space(3)))
; __global__ void __launch_bounds__(512, 2) fwd_megakernel(Args a) {
;     ...
;         LAS float* GT = (LAS float*)(lds + GT_OFF);
;         { const int t2 = pg8::tid_fresh(wave);
;           if (t2 < 64) { GT[t2] = a.in[6][t2]; GT[64 + t2] = a.in[7][t2]; }
;           if (t2 < 128) { GT[128 + t2] = a.in[13][t2]; GT[256 + t2] = a.in[14][t2]; GT[384 + t2] = a.in[17][t2]; GT[512 + t2] = a.in[18][t2]; } }
;         __syncthreads();
;         { const pg8::EpiQKV E{R, LDQ, CKV, D, GT, (LAS float*)(lds + XCH_OFF)};
;           pg8::Gemm g{XN, W_IN, M, DIN, D, D, MN, W_MEM, nullptr, nullptr}; pg8::DualOrder S; S.init(M, DIN, MMEM, D, G, bid);
;           pg8::gemm_phase<pg8::EpiQKV, pg8::DualOrder, true, true>(lds, g, S, E, wave); }
.LBB0_99:
	s_or_b64 exec, exec, s[4:5]
	s_mov_b32 s4, 0
	s_waitcnt lgkmcnt(0)
	s_barrier
	s_and_b32 s80, s39, 0xffffffc0
	v_mbcnt_lo_u32_b32 v0, -1, s4
	v_mbcnt_hi_u32_b32 v0, -1, v0
	v_add_u32_e32 v0, s80, v0
	v_cmp_gt_i32_e32 vcc, 64, v0
	v_ashrrev_i32_e32 v1, 31, v0
	s_and_saveexec_b64 s[4:5], vcc
	s_cbranch_execz .LBB0_101
	s_load_dwordx4 s[20:23], s[0:1], 0x30
	v_lshlrev_b64 v[2:3], 2, v[0:1]
	s_waitcnt lgkmcnt(0)
	v_lshl_add_u64 v[4:5], s[20:21], 0, v[2:3]
	v_lshl_add_u64 v[2:3], s[22:23], 0, v[2:3]
	global_load_dword v240, v[4:5], off
	global_load_dword v241, v[2:3], off
.LBB0_101:
	s_or_b64 exec, exec, s[4:5]
	s_movk_i32 s4, 0x80
	v_cmp_gt_i32_e32 vcc, s4, v0
	s_and_saveexec_b64 s[4:5], vcc
	s_cbranch_execz .LBB0_103
	s_load_dwordx4 s[20:23], s[0:1], 0x68
	s_load_dwordx4 s[40:43], s[0:1], 0x88
	v_lshlrev_b64 v[2:3], 2, v[0:1]
	s_waitcnt lgkmcnt(0)
	v_lshl_add_u64 v[4:5], s[20:21], 0, v[2:3]
	v_lshl_add_u64 v[6:7], s[22:23], 0, v[2:3]
	global_load_dword v242, v[4:5], off
	global_load_dword v243, v[6:7], off
	v_lshl_add_u64 v[4:5], s[40:41], 0, v[2:3]
	v_lshl_add_u64 v[2:3], s[42:43], 0, v[2:3]
	global_load_dword v244, v[4:5], off
	s_nop 0
	global_load_dword v245, v[2:3], off
.LBB0_103:
	s_or_b64 exec, exec, s[4:5]
	v_lshl_add_u32 v246, v0, 2, 0
	v_add_u32_e32 v246, 0x22000, v246
	v_mov_b32_e32 v248, v0
	s_mov_b32 s4, 0
	s_cmpk_gt_i32 s2, 0x67f
	v_mbcnt_lo_u32_b32 v0, -1, s4
	v_mbcnt_hi_u32_b32 v8, -1, v0
	v_add_u32_e32 v0, s80, v8
	s_nop 0
	v_readfirstlane_b32 s26, v0
	s_cbranch_scc0 .LBB0_106
	s_add_u32 s4, s2, 0xfffff980
	s_addc_u32 s5, 0, -1
	v_cmp_gt_u64_e64 s[6:7], s[4:5], 31
	s_mov_b64 s[18:19], 0
	s_and_b64 vcc, exec, s[6:7]
	s_cbranch_vccnz .LBB0_217
	s_and_b32 s40, s4, 7
	s_lshr_b32 s42, s4, 3
	s_mov_b64 s[4:5], 0
	s_mov_b32 s71, 1
	s_mov_b64 s[8:9], -1
	s_mov_b64 s[6:7], -1
	s_andn2_b64 vcc, exec, s[18:19]
	s_cbranch_vccz .LBB0_107
	s_branch .LBB0_108

; #define PG8_STAGE(bufoff, gbase, voff) do { _Pragma("unroll") for (int _i = 0; _i < 2; ++_i) \
;         __builtin_amdgcn_global_load_lds((const unsigned*)((const char*)(gbase) + (voff)[_i]), (PG8_LAS unsigned*)(lds + (bufoff) + ldsw + _i * 8192), 16, 0, 0); } while (0)
; #define PG8_WAIT_V(n) asm volatile("s_waitcnt vmcnt(" #n ")" ::: "memory")
; #define PG8_BAR __builtin_amdgcn_s_barrier()
; template <class Epi, class Sched, bool ALIGN_EPI = false, bool SP2 = false>
; __device__ __forceinline__ void gemm_phase(PG8_LAS unsigned char* lds, const Gemm g, const Sched& S, const Epi& E, int wave_id) {
;     ...
;         PG8_STAGE(PG8_SB(0, 0), cB, voffB); PG8_STAGE(PG8_SB(0, 1), cB + hstepB, voffB); PG8_STAGE(PG8_SA(0, 0), cA, voffA); PG8_STAGE(PG8_SA(0, 1), cA + hstepA, voffA);
;         if (wr == 1) PG8_BAR;
;         PG8_WAIT_V(2); PG8_BAR;
;         PG8_STAGE(PG8_SB(1, 0), cB + kstep, voffB); PG8_STAGE(PG8_SA(1, 0), cA + kstep, voffA); PG8_STAGE(PG8_SB(1, 1), cB + hstepB + kstep, voffB);
;         PG8_WAIT_V(6); PG8_BAR;
; __global__ void __launch_bounds__(512, 2) fwd_megakernel(Args a) {
;     ...
;           if (t2 < 64) { GT[t2] = a.in[6][t2]; GT[64 + t2] = a.in[7][t2]; }
;           if (t2 < 128) { GT[128 + t2] = a.in[13][t2]; GT[256 + t2] = a.in[14][t2]; GT[384 + t2] = a.in[17][t2]; GT[512 + t2] = a.in[18][t2]; } }
.LBB0_111:
	s_mov_b64 s[22:23], 0x80
	s_and_b32 s6, s8, 3
	s_add_i32 m0, s43, 0x18000
	v_lshl_add_u64 v[6:7], v[6:7], 0, s[22:23]
	s_lshl_b32 s7, s9, 13
	s_lshl_b32 s8, s6, 12
	s_waitcnt vmcnt(2)
	v_cmp_gt_i32_e64 s[100:101], 64, v248
	s_and_saveexec_b64 s[98:99], s[100:101]
	ds_write2st64_b32 v246, v240, v241 offset1:1
	s_or_b64 exec, exec, s[98:99]
	s_movk_i32 s100, 0x80
	v_cmp_gt_i32_e64 s[100:101], s100, v248
	s_and_saveexec_b64 s[98:99], s[100:101]
	ds_write2st64_b32 v246, v242, v243 offset0:2 offset1:4
	ds_write2st64_b32 v246, v244, v245 offset0:6 offset1:8
	s_or_b64 exec, exec, s[98:99]
	s_barrier
	global_load_lds_dwordx4 v[6:7], off
	v_lshl_add_u64 v[4:5], v[4:5], 0, s[22:23]
	s_add_i32 m0, s43, 0x1a000
	s_add_i32 s59, s43, 0x8000
	s_add_i32 s60, s43, 0xa000
	global_load_lds_dwordx4 v[4:5], off
	v_lshl_add_u64 v[0:1], v[0:1], 0, s[22:23]
	s_mov_b32 m0, s59
	s_add_u32 s4, s50, 0x40080
	global_load_lds_dwordx4 v[0:1], off
	v_lshl_add_u64 v[0:1], v[2:3], 0, s[22:23]
	s_mov_b32 m0, s60
	s_addc_u32 s5, s51, 0
	global_load_lds_dwordx4 v[0:1], off
	s_add_i32 m0, s43, 0x1c000
	v_lshl_add_u64 v[0:1], s[4:5], 0, v[138:139]
	global_load_lds_dwordx4 v[0:1], off
	v_lshl_add_u64 v[0:1], s[4:5], 0, v[142:143]
	s_add_i32 m0, s43, 0x1e000
	s_cmpk_lt_u32 s26, 0x100
	global_load_lds_dwordx4 v[0:1], off
	v_bfe_u32 v0, v8, 4, 2
	v_and_b32_e32 v1, 15, v8
	v_lshlrev_b32_e32 v3, 4, v0
	v_lshl_or_b32 v168, s9, 6, v1
	v_lshl_or_b32 v1, v1, 6, v3
	v_lshlrev_b32_e32 v3, 2, v8
	v_and_b32_e32 v3, 32, v3
	s_cselect_b64 s[30:31], -1, 0
	s_cmp_lt_u32 s6, 2
	v_lshlrev_b32_e32 v2, 3, v0
	v_bitop3_b32 v4, v1, s7, v3 bitop3:0xde
	v_bitop3_b32 v169, v1, s8, v3 bitop3:0xde
	v_cmp_eq_u32_e64 s[8:9], 0, v0
	v_lshlrev_b32_e32 v0, 5, v168
	s_cselect_b64 s[4:5], -1, 0
	s_add_i32 s7, 0, 0x20000
	v_add_u32_e32 v171, s7, v0
	s_add_i32 s7, 0, 0x20200
	v_add_u32_e32 v173, s7, v0
	s_add_i32 s7, 0, 0x20400
	v_add_u32_e32 v175, s7, v0
	s_add_i32 s7, 0, 0x20600
	v_add_u32_e32 v177, s7, v0
	s_add_i32 s7, 0, 0x21000
	v_add_u32_e32 v179, s7, v0
	s_add_i32 s7, 0, 0x21200
	v_add_u32_e32 v181, s7, v0
	s_add_i32 s7, 0, 0x21400
	v_add_u32_e32 v183, s7, v0
	s_add_i32 s7, 0, 0x21600
	v_add_u32_e32 v185, s7, v0
	v_lshlrev_b32_e32 v0, 14, v9
	v_and_b32_e32 v0, 0xffff8000, v0
	v_lshl_add_u32 v0, v10, 11, v0
	v_and_b32_e32 v1, 1, v9
	v_lshl_or_b32 v0, v1, 6, v0
	v_lshl_add_u32 v144, v11, 1, v0
	v_lshlrev_b32_e32 v0, 14, v12
	v_and_b32_e32 v0, 0xffff8000, v0
	s_waitcnt vmcnt(6)
	v_lshl_add_u32 v0, v13, 11, v0
	v_and_b32_e32 v1, 1, v12
	v_lshl_or_b32 v170, s6, 5, v2
	s_lshl_b32 s6, s6, 2
	v_lshl_or_b32 v0, v1, 6, v0
	s_add_i32 s66, 0, 0x10000
	s_add_i32 s67, 0, 0x14000
	s_ashr_i32 s61, s24, 31
	s_mov_b32 s62, s24
	s_ashr_i32 s63, s2, 31
	v_add_u32_e32 v172, s6, v171
	v_add_u32_e32 v174, s6, v173
	v_add_u32_e32 v176, s6, v175
	v_add_u32_e32 v178, s6, v177
	v_add_u32_e32 v180, s6, v179
	v_add_u32_e32 v182, s6, v181
	v_add_u32_e32 v184, s6, v183
	v_add_u32_e32 v186, s6, v185
	v_mov_b32_e32 v145, v139
	v_lshl_add_u32 v146, v14, 1, v0
	v_mov_b32_e32 v147, v139
	v_mov_b64_e32 v[148:149], 0x67f
	s_movk_i32 s65, 0xd1
	v_add_u32_e32 v187, s66, v169
	v_add_u32_e32 v188, s67, v169
	v_add_u32_e32 v189, 0, v4
	s_movk_i32 s68, 0x180
	s_movk_i32 s69, 0x1a00
	v_mov_b32_e32 v190, 0x3e0293ee
	v_bfrev_b32_e32 v191, 60
	v_mov_b32_e32 v192, 0x3c800000
	s_barrier
	s_branch .LBB0_114

; #define LAS __attribute__((address_space(3)))
; #define SCHED_FENCE() __builtin_amdgcn_sched_barrier(0)
; #define LOADA(tt) do { const char* kp_ = kgp + (size_t)(tt) * tstep; const char* vp_ = vgp + (size_t)(tt) * tstep; ka0 = *(const u32x4*)kp_; ka1 = *(const u32x4*)(kp_ + 16); va0 = *(const u32x4*)vp_; va1 = *(const u32x4*)(vp_ + 16); } while (0)
; template <int NC, bool DIAG>
; __device__ __forceinline__ void attn_tile(f32x16 (&O)[4], float& l, const bf16x8* Q, const LAS char* Kb, const LAS char* Vb, int r32, int hi, int lane, float qd, int k0, int qw, float nslope, float negM0) {
;     ...
;     const int k1 = k0 + 32;
;     if (NC == 2) {
;         const float ns0 = (k0 < qw) ? nslope : ((k0 > qw) ? -nslope : 0.f), ns1 = (k1 < qw) ? nslope : ((k1 > qw) ? -nslope : 0.f);
;         const float b0 = fmaf(ns0, qd - (float)k0, negM0), b1 = fmaf(ns1, qd - (float)k1, negM0);
; #pragma unroll
;         for (int r = 0; r < 16; ++r) { S0[r] = fmaf(-ns0, (float)((r & 3) + 8 * (r >> 2)), b0); S1[r] = fmaf(-ns1, (float)((r & 3) + 8 * (r >> 2)), b1); }
;     } else {
; #pragma unroll
;         for (int r = 0; r < 16; ++r) { S0[r] = negM0; S1[r] = negM0; }
;     }
;     VFrag vf0, vf1;
;     if (NC == 2) {
;         bf16x8 kf0[NQ], kf1[NQ];
;         kload32<NQ>(kf0, Kb, r32, hi);
;         SCHED_FENCE();
;         qkmm32<NQ>(S0, kf0, Q);
;         kload32<NQ>(kf1, Kb + 32 * KP, r32, hi);
;         vload16<0>(vf0, Vb, lane);
;         SCHED_FENCE();
;         qkmm32<NQ>(S1, kf1, Q);
; template <int NC>
; __device__ __forceinline__ void attn_shared_unit(LAS char* lds, bf16* qbase, const bf16* Kg, const bf16* Vg, int kvp, int nt, int qpos, int qw, float nslope, float negM0, float lam, const float* subln, int wave_id) {
;     ...
;     for (int t = t_lo; t < t_hi; t += 2) {
;         {
;             if (t + 2 < t_hi) LOADA(t + 2);
;             int k0v = t * 64; asm volatile("" : "+s"(k0v));
;             const LAS char* Kb = lds + cm * 128; const LAS char* Vb = lds + 64 * KP;
;             if (t == td) attn_tile<NC, true>(O, l, Q, Kb, Vb, r32, hi, lane, qd, k0v, qw, nslope, negM0);
;             else attn_tile<NC, false>(O, l, Q, Kb, Vb, r32, hi, lane, qd, k0v, qw, nslope, negM0);
.LBB0_273:
	ds_read_b128 v[80:83], v227
	ds_read_b128 v[84:87], v227 offset:32
	ds_read_b128 v[88:91], v227 offset:64
	ds_read_b128 v[92:95], v227 offset:96
	s_add_i32 s90, s88, -1
	s_cmp_lt_i32 s90, s57
	s_cselect_b64 s[60:61], -1, 0
	s_cmp_ge_i32 s90, s57
	s_cbranch_scc1 .LBB0_275
	s_mov_b32 s4, 0xfff2fbf0
	s_mov_b32 s5, -1
	v_lshl_add_u64 v[64:65], v[216:217], 0, s[4:5]
	s_mov_b32 s4, 0xfff2fff0
	v_add_co_u32_e32 v68, vcc, 0xfff30000, v216
	s_mov_b32 s5, -1
	s_nop 0
	v_addc_co_u32_e32 v69, vcc, -1, v217, vcc
	v_lshl_add_u64 v[66:67], v[216:217], 0, s[4:5]
	global_load_dwordx4 v[178:181], v[68:69], off offset:-1040
	global_load_dwordx4 v[194:197], v[68:69], off offset:-16
	global_load_dwordx4 v[190:193], v[64:65], off offset:16
	global_load_dwordx4 v[202:205], v[66:67], off offset:16
.LBB0_275:
	s_sub_i32 s27, s89, 64
	s_add_i32 s91, s85, s88
	s_add_i32 s26, s27, 32
	s_cmp_lt_i32 s27, s87
	s_cselect_b64 vcc, -1, 0
	s_cmp_gt_i32 s27, s87
	s_cselect_b64 s[78:79], -1, 0
	v_cndmask_b32_e64 v64, 0, -v225, s[78:79]
	s_cmp_lt_i32 s26, s87
	v_cndmask_b32_e32 v218, v64, v225, vcc
	v_cvt_f32_i32_e32 v64, s27
	v_cvt_f32_i32_e32 v66, s26
	s_cselect_b64 s[4:5], -1, 0
	s_cmp_gt_i32 s26, s87
	s_cselect_b64 s[92:93], -1, 0
	v_cndmask_b32_e64 v65, 0, -v225, s[92:93]
	v_cndmask_b32_e64 v220, v65, v225, s[4:5]
	v_sub_f32_e32 v231, v219, v64
	v_sub_f32_e32 v230, v219, v66
	v_fma_f32 v222, v218, v231, v254
	v_fma_f32 v224, v220, v230, v254
	s_cmp_lg_u32 s91, 3
	v_fmamk_f32 v144, v218, 0x80000000, v222
	v_fmamk_f32 v128, v220, 0x80000000, v224
	s_mov_b64 s[4:5], -1
	v_sub_f32_e32 v145, v222, v218
	v_sub_f32_e32 v129, v224, v220
	s_cbranch_scc0 .LBB0_277
	v_pk_fma_f32 v[146:147], v[218:219], s[22:23], v[222:223] op_sel_hi:[0,1,0] neg_lo:[1,0,0] neg_hi:[1,0,0]
	v_pk_fma_f32 v[130:131], v[220:221], s[22:23], v[224:225] op_sel_hi:[0,1,0] neg_lo:[1,0,0] neg_hi:[1,0,0]
	v_pk_fma_f32 v[148:149], v[218:219], s[44:45], v[222:223] op_sel_hi:[0,1,0] neg_lo:[1,0,0] neg_hi:[1,0,0]
	v_pk_fma_f32 v[132:133], v[220:221], s[44:45], v[224:225] op_sel_hi:[0,1,0] neg_lo:[1,0,0] neg_hi:[1,0,0]
	v_pk_fma_f32 v[150:151], v[218:219], s[46:47], v[222:223] op_sel_hi:[0,1,0] neg_lo:[1,0,0] neg_hi:[1,0,0]
	v_pk_fma_f32 v[134:135], v[220:221], s[46:47], v[224:225] op_sel_hi:[0,1,0] neg_lo:[1,0,0] neg_hi:[1,0,0]
	v_pk_fma_f32 v[152:153], v[218:219], s[48:49], v[222:223] op_sel_hi:[0,1,0] neg_lo:[1,0,0] neg_hi:[1,0,0]
	v_pk_fma_f32 v[136:137], v[220:221], s[48:49], v[224:225] op_sel_hi:[0,1,0] neg_lo:[1,0,0] neg_hi:[1,0,0]
	v_pk_fma_f32 v[154:155], v[218:219], s[50:51], v[222:223] op_sel_hi:[0,1,0] neg_lo:[1,0,0] neg_hi:[1,0,0]
	v_pk_fma_f32 v[138:139], v[220:221], s[50:51], v[224:225] op_sel_hi:[0,1,0] neg_lo:[1,0,0] neg_hi:[1,0,0]
	v_pk_fma_f32 v[156:157], v[218:219], s[52:53], v[222:223] op_sel_hi:[0,1,0] neg_lo:[1,0,0] neg_hi:[1,0,0]
	v_pk_fma_f32 v[140:141], v[220:221], s[52:53], v[224:225] op_sel_hi:[0,1,0] neg_lo:[1,0,0] neg_hi:[1,0,0]
	v_pk_fma_f32 v[158:159], v[218:219], s[54:55], v[222:223] op_sel_hi:[0,1,0] neg_lo:[1,0,0] neg_hi:[1,0,0]
	v_pk_fma_f32 v[142:143], v[220:221], s[54:55], v[224:225] op_sel_hi:[0,1,0] neg_lo:[1,0,0] neg_hi:[1,0,0]
	s_waitcnt lgkmcnt(3)
	s_nop 0
	v_mfma_f32_32x32x16_bf16 v[64:79], v[80:83], v[162:165], v[144:159]
	s_waitcnt lgkmcnt(2)
	v_mfma_f32_32x32x16_bf16 v[64:79], v[84:87], v[166:169], v[64:79]
	s_waitcnt lgkmcnt(1)
	v_mfma_f32_32x32x16_bf16 v[64:79], v[88:91], v[170:173], v[64:79]
	s_waitcnt lgkmcnt(0)
	v_mfma_f32_32x32x16_bf16 v[64:79], v[92:95], v[174:177], v[64:79]
	ds_read_b128 v[80:83], v227 offset:8704
	ds_read_b128 v[84:87], v227 offset:8736
	ds_read_b128 v[88:91], v227 offset:8768
	ds_read_b128 v[92:95], v227 offset:8800
	ds_read_b64_tr_b16 v[96:97], v226 offset:17408
	ds_read_b64_tr_b16 v[98:99], v226 offset:19968
	ds_read_b64_tr_b16 v[100:101], v226 offset:17472
	ds_read_b64_tr_b16 v[102:103], v226 offset:20032
	ds_read_b64_tr_b16 v[112:113], v226 offset:17536
	ds_read_b64_tr_b16 v[114:115], v226 offset:20096
	ds_read_b64_tr_b16 v[232:233], v226 offset:17600
	ds_read_b64_tr_b16 v[234:235], v226 offset:20160
	v_exp_f32_e32 v64, v64
	v_exp_f32_e32 v65, v65
	s_waitcnt lgkmcnt(11)
	v_mfma_f32_32x32x16_bf16 v[146:161], v[80:83], v[162:165], v[128:143]
	v_exp_f32_e32 v66, v66
	v_exp_f32_e32 v67, v67
	v_add_f32_e32 v104, v229, v64
	v_exp_f32_e32 v68, v68
	v_add_f32_e32 v80, v65, v104
	v_exp_f32_e32 v69, v69
	v_add_f32_e32 v80, v66, v80
	s_waitcnt lgkmcnt(10)
; #define SCHED_FENCE() __builtin_amdgcn_sched_barrier(0)
; template <int NC, bool DIAG>
; __device__ __forceinline__ void attn_tile(f32x16 (&O)[4], float& l, const bf16x8* Q, const LAS char* Kb, const LAS char* Vb, int r32, int hi, int lane, float qd, int k0, int qw, float nslope, float negM0) {
;     ...
;         qkmm32<NQ>(S1, kf1, Q);
;         if (DIAG) { const float nd = (k0 == qw) ? nslope : 0.f;
; #pragma unroll
;             for (int r = 0; r < 16; ++r) S0[r] = fmaf(nd, fabsf(qd - (float)k0 - (float)((r & 3) + 8 * (r >> 2))), S0[r]); }
;         soft32<0>(S0, P0, l, 0.f, 0.f);
;         vload16<1>(vf0, Vb, lane);
;         SCHED_FENCE();
;     } else {
;         bf16x8 kf[NQ];
;         kload32<NQ>(kf, Kb, r32, hi);
;         SCHED_FENCE();
;         qkmm32<NQ>(S0, kf, Q);
;         kload32<NQ>(kf, Kb + 32 * KP, r32, hi);
;         vload32(vf0, Vb, lane);
;         SCHED_FENCE();
;         qkmm32<NQ>(S1, kf, Q);
;         soft32<0>(S0, P0, l, 0.f, 0.f);
;         SCHED_FENCE();
;     }
;     pvmm32(O, P0, vf0);
;     if (NC == 2 && DIAG) { const float nd = (k1 == qw) ? nslope : 0.f;
; #pragma unroll
;         for (int r = 0; r < 16; ++r) S1[r] = fmaf(nd, fabsf(qd - (float)k1 - (float)((r & 3) + 8 * (r >> 2))), S1[r]); }
;     soft32<0>(S1, P1, l, 0.f, 0.f);
;     if (NC == 2) {
;     vload16<0>(vf1, Vb + 32 * VP, lane);
;     SCHED_FENCE();
;     vload16<1>(vf1, Vb + 32 * VP, lane);
;     } else {
;     vload32(vf1, Vb + 32 * VP, lane);
;     SCHED_FENCE();
;     }
;     pvmm32(O, P1, vf1);
	v_mfma_f32_32x32x16_bf16 v[146:161], v[84:87], v[166:169], v[146:161]
	v_exp_f32_e32 v70, v70
	v_add_f32_e32 v80, v67, v80
	v_exp_f32_e32 v71, v71
	v_add_f32_e32 v80, v68, v80
	v_exp_f32_e32 v72, v72
	v_add_f32_e32 v80, v69, v80
	v_exp_f32_e32 v73, v73
	ds_read_b64_tr_b16 v[134:135], v226 offset:22528
	ds_read_b64_tr_b16 v[138:139], v226 offset:22592
	ds_read_b64_tr_b16 v[236:237], v226 offset:22656
	ds_read_b64_tr_b16 v[240:241], v226 offset:22720
	ds_read_b64_tr_b16 v[136:137], v226 offset:25088
	ds_read_b64_tr_b16 v[140:141], v226 offset:25152
	ds_read_b64_tr_b16 v[238:239], v226 offset:25216
	ds_read_b64_tr_b16 v[242:243], v226 offset:25280
	v_add_f32_e32 v80, v70, v80
	v_exp_f32_e32 v74, v74
	v_add_f32_e32 v80, v71, v80
	v_exp_f32_e32 v75, v75
	s_waitcnt lgkmcnt(14)
	v_mfma_f32_32x32x16_bf16 v[146:161], v[88:91], v[170:173], v[146:161]
	v_add_f32_e32 v80, v72, v80
	v_exp_f32_e32 v76, v76
	v_add_f32_e32 v80, v73, v80
	v_exp_f32_e32 v77, v77
	v_add_f32_e32 v80, v74, v80
	v_exp_f32_e32 v78, v78
	v_add_f32_e32 v80, v75, v80
	v_exp_f32_e32 v79, v79
	v_add_f32_e32 v80, v76, v80
	v_add_f32_e32 v80, v77, v80
	v_add_f32_e32 v80, v78, v80
	v_add_f32_e32 v80, v79, v80
	v_mfma_f32_32x32x16_bf16 v[146:161], v[92:95], v[174:177], v[146:161]
	v_cvt_pk_bf16_f32 v130, v64, v65
	v_cvt_pk_bf16_f32 v131, v66, v67
	v_cvt_pk_bf16_f32 v132, v68, v69
	v_cvt_pk_bf16_f32 v133, v70, v71
	v_cvt_pk_bf16_f32 v244, v72, v73
	v_cvt_pk_bf16_f32 v245, v74, v75
	v_cvt_pk_bf16_f32 v246, v76, v77
	v_cvt_pk_bf16_f32 v247, v78, v79
	s_nop 3
	v_exp_f32_e32 v142, v146
	v_exp_f32_e32 v143, v147
	v_exp_f32_e32 v146, v148
	v_exp_f32_e32 v147, v149
	v_mfma_f32_32x32x16_bf16 v[64:79], v[96:99], v[130:133], v[48:63]
	v_add_f32_e32 v96, v80, v142
	v_exp_f32_e32 v148, v150
	v_add_f32_e32 v96, v143, v96
	v_exp_f32_e32 v149, v151
	v_add_f32_e32 v96, v146, v96
	v_exp_f32_e32 v150, v152
	v_add_f32_e32 v116, v147, v96
	v_exp_f32_e32 v151, v153
	s_waitcnt lgkmcnt(12)
	v_mfma_f32_32x32x16_bf16 v[80:95], v[100:103], v[130:133], v[32:47]
	v_exp_f32_e32 v153, v154
	v_exp_f32_e32 v154, v155
	v_exp_f32_e32 v155, v156
	v_exp_f32_e32 v156, v157
	v_exp_f32_e32 v157, v159
	s_waitcnt lgkmcnt(10)
	v_mfma_f32_32x32x16_bf16 v[96:111], v[112:115], v[130:133], v[16:31]
	v_add_f32_e32 v112, v148, v116
	v_add_f32_e32 v112, v149, v112
	v_add_f32_e32 v112, v150, v112
	v_add_f32_e32 v152, v151, v112
	s_waitcnt lgkmcnt(8)
	v_mfma_f32_32x32x16_bf16 v[112:127], v[232:235], v[130:133], v[0:15]
	v_add_f32_e32 v130, v153, v152
	v_exp_f32_e32 v152, v158
	v_add_f32_e32 v130, v154, v130
	v_add_f32_e32 v130, v155, v130
	v_add_f32_e32 v130, v156, v130
	v_add_f32_e32 v130, v152, v130
	v_add_f32_e32 v130, v157, v130
	s_waitcnt lgkmcnt(3)
	v_mfma_f32_32x32x16_bf16 v[64:79], v[134:137], v[244:247], v[64:79]
	v_cvt_pk_bf16_f32 v131, v146, v147
	v_cvt_pk_bf16_f32 v132, v148, v149
	v_cvt_pk_bf16_f32 v133, v150, v151
	v_cvt_pk_bf16_f32 v134, v153, v154
	v_cvt_pk_bf16_f32 v135, v155, v156
	v_cvt_pk_bf16_f32 v136, v152, v157
	v_exp_f32_e32 v137, v160
	s_waitcnt lgkmcnt(2)
	v_mfma_f32_32x32x16_bf16 v[80:95], v[138:141], v[244:247], v[80:95]
	ds_read_b64_tr_b16 v[138:139], v226 offset:27648
	ds_read_b64_tr_b16 v[146:147], v226 offset:27712
	ds_read_b64_tr_b16 v[150:151], v226 offset:27776
	ds_read_b64_tr_b16 v[154:155], v226 offset:27840
	ds_read_b64_tr_b16 v[140:141], v226 offset:30208
	ds_read_b64_tr_b16 v[148:149], v226 offset:30272
	ds_read_b64_tr_b16 v[152:153], v226 offset:30336
	ds_read_b64_tr_b16 v[156:157], v226 offset:30400
	v_exp_f32_e32 v158, v161
	v_add_f32_e32 v130, v137, v130
	v_add_f32_e32 v232, v158, v130
	v_cvt_pk_bf16_f32 v130, v142, v143
	s_waitcnt lgkmcnt(9)
	v_mfma_f32_32x32x16_bf16 v[96:111], v[236:239], v[244:247], v[96:111]
	v_cvt_pk_bf16_f32 v137, v137, v158
	s_waitcnt lgkmcnt(8)
	v_mfma_f32_32x32x16_bf16 v[112:127], v[240:243], v[244:247], v[112:127]
	s_waitcnt lgkmcnt(3)
	v_mfma_f32_32x32x16_bf16 v[64:79], v[138:141], v[130:133], v[64:79]
	ds_read_b64_tr_b16 v[140:141], v226 offset:35328
	s_mov_b64 s[4:5], 0
	s_waitcnt lgkmcnt(3)
	v_mfma_f32_32x32x16_bf16 v[80:95], v[146:149], v[130:133], v[80:95]
	s_waitcnt lgkmcnt(2)
	v_mfma_f32_32x32x16_bf16 v[96:111], v[150:153], v[130:133], v[96:111]
	s_waitcnt lgkmcnt(1)
	v_mfma_f32_32x32x16_bf16 v[112:127], v[154:157], v[130:133], v[112:127]
	ds_read_b64_tr_b16 v[138:139], v226 offset:32768
	ds_read_b64_tr_b16 v[130:131], v226 offset:32832
	ds_read_b64_tr_b16 v[146:147], v226 offset:32896
	ds_read_b64_tr_b16 v[150:151], v226 offset:32960
	ds_read_b64_tr_b16 v[132:133], v226 offset:35392
	ds_read_b64_tr_b16 v[148:149], v226 offset:35456
	ds_read_b64_tr_b16 v[152:153], v226 offset:35520
	s_waitcnt lgkmcnt(6)
	v_mfma_f32_32x32x16_bf16 v[64:79], v[138:141], v[134:137], v[64:79]
	s_waitcnt lgkmcnt(2)
	v_mfma_f32_32x32x16_bf16 v[80:95], v[130:133], v[134:137], v[80:95]
	s_waitcnt lgkmcnt(1)
	v_mfma_f32_32x32x16_bf16 v[96:111], v[146:149], v[134:137], v[96:111]
	s_waitcnt lgkmcnt(0)
	v_mfma_f32_32x32x16_bf16 v[112:127], v[150:153], v[134:137], v[112:127]

; #define LAS __attribute__((address_space(3)))
; #define SCHED_FENCE() __builtin_amdgcn_sched_barrier(0)
; template <int NC, bool DIAG>
; __device__ __forceinline__ void attn_tile(f32x16 (&O)[4], float& l, const bf16x8* Q, const LAS char* Kb, const LAS char* Vb, int r32, int hi, int lane, float qd, int k0, int qw, float nslope, float negM0) {
;     ...
;     const int k1 = k0 + 32;
;     if (NC == 2) {
;         const float ns0 = (k0 < qw) ? nslope : ((k0 > qw) ? -nslope : 0.f), ns1 = (k1 < qw) ? nslope : ((k1 > qw) ? -nslope : 0.f);
;         const float b0 = fmaf(ns0, qd - (float)k0, negM0), b1 = fmaf(ns1, qd - (float)k1, negM0);
; #pragma unroll
;         for (int r = 0; r < 16; ++r) { S0[r] = fmaf(-ns0, (float)((r & 3) + 8 * (r >> 2)), b0); S1[r] = fmaf(-ns1, (float)((r & 3) + 8 * (r >> 2)), b1); }
;     } else {
; #pragma unroll
;         for (int r = 0; r < 16; ++r) { S0[r] = negM0; S1[r] = negM0; }
;     }
;     VFrag vf0, vf1;
;     if (NC == 2) {
;         bf16x8 kf0[NQ], kf1[NQ];
;         kload32<NQ>(kf0, Kb, r32, hi);
;         SCHED_FENCE();
;         qkmm32<NQ>(S0, kf0, Q);
;         kload32<NQ>(kf1, Kb + 32 * KP, r32, hi);
;         vload16<0>(vf0, Vb, lane);
;         SCHED_FENCE();
;         qkmm32<NQ>(S1, kf1, Q);
;         if (DIAG) { const float nd = (k0 == qw) ? nslope : 0.f;
; #pragma unroll
;             for (int r = 0; r < 16; ++r) S0[r] = fmaf(nd, fabsf(qd - (float)k0 - (float)((r & 3) + 8 * (r >> 2))), S0[r]); }
;         soft32<0>(S0, P0, l, 0.f, 0.f);
;         vload16<1>(vf0, Vb, lane);
; template <int NC>
; __device__ __forceinline__ void attn_shared_unit(LAS char* lds, bf16* qbase, const bf16* Kg, const bf16* Vg, int kvp, int nt, int qpos, int qw, float nslope, float negM0, float lam, const float* subln, int wave_id) {
;     ...
;             if (t + 3 < t_hi) LOADB(t + 3);
;             int k0v = (t + 1) * 64; asm volatile("" : "+s"(k0v));
;             const LAS char* Kb = lds + BUFB + cm * 128; const LAS char* Vb = lds + BUFB + 64 * KP;
;             if (t + 1 == td) attn_tile<NC, true>(O, l, Q, Kb, Vb, r32, hi, lane, qd, k0v, qw, nslope, negM0);
;             else attn_tile<NC, false>(O, l, Q, Kb, Vb, r32, hi, lane, qd, k0v, qw, nslope, negM0);
.LBB0_281:
	ds_read_b128 v[16:19], v227 offset:37888
	ds_read_b128 v[20:23], v227 offset:37920
	ds_read_b128 v[24:27], v227 offset:37952
	ds_read_b128 v[28:31], v227 offset:37984
	s_mov_b32 s26, s89
	s_add_i32 s78, s26, 32
	s_cmp_lt_i32 s26, s87
	s_cselect_b64 vcc, -1, 0
	s_cmp_gt_i32 s26, s87
	s_cselect_b64 s[4:5], -1, 0
	v_cndmask_b32_e64 v0, 0, -v225, s[4:5]
	s_cmp_lt_i32 s78, s87
	v_cndmask_b32_e32 v218, v0, v225, vcc
	v_cvt_f32_i32_e32 v0, s26
	v_cvt_f32_i32_e32 v2, s78
	s_cselect_b64 s[4:5], -1, 0
	s_cmp_gt_i32 s78, s87
	s_cselect_b64 s[92:93], -1, 0
	v_cndmask_b32_e64 v1, 0, -v225, s[92:93]
	v_cndmask_b32_e64 v220, v1, v225, s[4:5]
	v_sub_f32_e32 v234, v219, v0
	v_sub_f32_e32 v233, v219, v2
	v_fma_f32 v142, v218, v234, v254
	v_fma_f32 v224, v220, v233, v254
	s_cmp_lg_u32 s91, 2
	v_fmamk_f32 v144, v218, 0x80000000, v142
	v_fmamk_f32 v128, v220, 0x80000000, v224
	s_mov_b64 s[4:5], -1
	v_sub_f32_e32 v145, v142, v218
	v_sub_f32_e32 v129, v224, v220
	s_cbranch_scc0 .LBB0_284
	v_pk_fma_f32 v[146:147], v[218:219], s[22:23], v[142:143] op_sel_hi:[0,1,0] neg_lo:[1,0,0] neg_hi:[1,0,0]
	v_pk_fma_f32 v[148:149], v[218:219], s[44:45], v[142:143] op_sel_hi:[0,1,0] neg_lo:[1,0,0] neg_hi:[1,0,0]
	v_pk_fma_f32 v[150:151], v[218:219], s[46:47], v[142:143] op_sel_hi:[0,1,0] neg_lo:[1,0,0] neg_hi:[1,0,0]
	v_pk_fma_f32 v[152:153], v[218:219], s[48:49], v[142:143] op_sel_hi:[0,1,0] neg_lo:[1,0,0] neg_hi:[1,0,0]
	v_pk_fma_f32 v[154:155], v[218:219], s[50:51], v[142:143] op_sel_hi:[0,1,0] neg_lo:[1,0,0] neg_hi:[1,0,0]
	v_pk_fma_f32 v[156:157], v[218:219], s[52:53], v[142:143] op_sel_hi:[0,1,0] neg_lo:[1,0,0] neg_hi:[1,0,0]
	v_pk_fma_f32 v[158:159], v[218:219], s[54:55], v[142:143] op_sel_hi:[0,1,0] neg_lo:[1,0,0] neg_hi:[1,0,0]
	v_pk_fma_f32 v[142:143], v[220:221], s[54:55], v[224:225] op_sel_hi:[0,1,0] neg_lo:[1,0,0] neg_hi:[1,0,0]
	v_pk_fma_f32 v[130:131], v[220:221], s[22:23], v[224:225] op_sel_hi:[0,1,0] neg_lo:[1,0,0] neg_hi:[1,0,0]
	v_pk_fma_f32 v[132:133], v[220:221], s[44:45], v[224:225] op_sel_hi:[0,1,0] neg_lo:[1,0,0] neg_hi:[1,0,0]
	v_pk_fma_f32 v[134:135], v[220:221], s[46:47], v[224:225] op_sel_hi:[0,1,0] neg_lo:[1,0,0] neg_hi:[1,0,0]
	v_pk_fma_f32 v[136:137], v[220:221], s[48:49], v[224:225] op_sel_hi:[0,1,0] neg_lo:[1,0,0] neg_hi:[1,0,0]
	v_pk_fma_f32 v[138:139], v[220:221], s[50:51], v[224:225] op_sel_hi:[0,1,0] neg_lo:[1,0,0] neg_hi:[1,0,0]
	v_pk_fma_f32 v[140:141], v[220:221], s[52:53], v[224:225] op_sel_hi:[0,1,0] neg_lo:[1,0,0] neg_hi:[1,0,0]
	s_waitcnt lgkmcnt(3)
	s_nop 0
	v_mfma_f32_32x32x16_bf16 v[0:15], v[16:19], v[162:165], v[144:159]
	s_waitcnt lgkmcnt(2)
	v_mfma_f32_32x32x16_bf16 v[0:15], v[20:23], v[166:169], v[0:15]
	ds_read_b128 v[16:19], v227 offset:46592
	ds_read_b128 v[20:23], v227 offset:46624
	ds_read_b128 v[32:35], v227 offset:46656
	ds_read_b128 v[36:39], v227 offset:46688
	s_waitcnt lgkmcnt(5)
	v_mfma_f32_32x32x16_bf16 v[0:15], v[24:27], v[170:173], v[0:15]
	ds_read_b64_tr_b16 v[24:25], v226 offset:55296
	ds_read_b64_tr_b16 v[236:237], v226 offset:55360
	ds_read_b64_tr_b16 v[240:241], v226 offset:55424
	ds_read_b64_tr_b16 v[244:245], v226 offset:55488
	ds_read_b64_tr_b16 v[26:27], v226 offset:57856
	ds_read_b64_tr_b16 v[238:239], v226 offset:57920
	ds_read_b64_tr_b16 v[242:243], v226 offset:57984
	ds_read_b64_tr_b16 v[246:247], v226 offset:58048
	s_waitcnt lgkmcnt(12)
	v_mfma_f32_32x32x16_bf16 v[0:15], v[28:31], v[174:177], v[0:15]
	s_nop 11
	v_exp_f32_e32 v0, v0
	v_exp_f32_e32 v1, v1
	s_waitcnt lgkmcnt(11)
	v_mfma_f32_32x32x16_bf16 v[146:161], v[16:19], v[162:165], v[128:143]
	v_exp_f32_e32 v2, v2
	v_exp_f32_e32 v3, v3
	v_add_f32_e32 v28, v232, v0
	v_exp_f32_e32 v4, v4
	v_add_f32_e32 v16, v1, v28
	v_exp_f32_e32 v5, v5
	v_add_f32_e32 v16, v2, v16
	s_waitcnt lgkmcnt(10)
	v_mfma_f32_32x32x16_bf16 v[146:161], v[20:23], v[166:169], v[146:161]
	v_exp_f32_e32 v6, v6
	v_add_f32_e32 v16, v3, v16
	v_exp_f32_e32 v7, v7
	v_mov_b64_e32 v[230:231], v[208:209]
	s_waitcnt vmcnt(1)
	v_mov_b64_e32 v[208:209], v[200:201]
	v_add_f32_e32 v16, v4, v16
	v_exp_f32_e32 v8, v8
	s_waitcnt lgkmcnt(9)
	v_mfma_f32_32x32x16_bf16 v[146:161], v[32:35], v[170:173], v[146:161]
	v_mov_b64_e32 v[206:207], v[198:199]
	v_mov_b64_e32 v[200:201], v[188:189]
	v_add_f32_e32 v16, v5, v16
	v_exp_f32_e32 v9, v9
	v_mov_b64_e32 v[198:199], v[186:187]
	v_mov_b64_e32 v[188:189], v[184:185]
	v_add_f32_e32 v16, v6, v16
	v_exp_f32_e32 v10, v10
	v_mov_b64_e32 v[186:187], v[182:183]
	v_mov_b64_e32 v[182:183], v[194:195]
	v_add_f32_e32 v16, v7, v16
	v_exp_f32_e32 v11, v11
	v_mov_b64_e32 v[184:185], v[196:197]
	v_mov_b64_e32 v[196:197], v[180:181]
	v_add_f32_e32 v16, v8, v16
	v_exp_f32_e32 v12, v12
	ds_read_b64_tr_b16 v[134:135], v226 offset:60416
	ds_read_b64_tr_b16 v[138:139], v226 offset:60480
	ds_read_b64_tr_b16 v[248:249], v226 offset:60544
	v_mov_b64_e32 v[194:195], v[178:179]
	ds_read_b64_tr_b16 v[178:179], v226 offset:60608
	ds_read_b64_tr_b16 v[136:137], v226 offset:62976
	ds_read_b64_tr_b16 v[140:141], v226 offset:63040
	ds_read_b64_tr_b16 v[250:251], v226 offset:63104
	ds_read_b64_tr_b16 v[180:181], v226 offset:63168
	v_mov_b64_e32 v[222:223], v[216:217]
	v_mov_b64_e32 v[216:217], v[176:177]
	v_add_f32_e32 v16, v9, v16
	v_exp_f32_e32 v13, v13
	s_waitcnt lgkmcnt(14)
; #define SCHED_FENCE() __builtin_amdgcn_sched_barrier(0)
; #define LOADB(tt) do { const char* kp_ = kgp + (size_t)(tt) * tstep; const char* vp_ = vgp + (size_t)(tt) * tstep; kb0 = *(const u32x4*)kp_; kb1 = *(const u32x4*)(kp_ + 16); vb0 = *(const u32x4*)vp_; vb1 = *(const u32x4*)(vp_ + 16); } while (0)
; template <int NC, bool DIAG>
; __device__ __forceinline__ void attn_tile(f32x16 (&O)[4], float& l, const bf16x8* Q, const LAS char* Kb, const LAS char* Vb, int r32, int hi, int lane, float qd, int k0, int qw, float nslope, float negM0) {
;     ...
;     pvmm32(O, P0, vf0);
;     if (NC == 2 && DIAG) { const float nd = (k1 == qw) ? nslope : 0.f;
; #pragma unroll
;         for (int r = 0; r < 16; ++r) S1[r] = fmaf(nd, fabsf(qd - (float)k1 - (float)((r & 3) + 8 * (r >> 2))), S1[r]); }
;     soft32<0>(S1, P1, l, 0.f, 0.f);
;     if (NC == 2) {
;     vload16<0>(vf1, Vb + 32 * VP, lane);
;     SCHED_FENCE();
;     vload16<1>(vf1, Vb + 32 * VP, lane);
;     } else {
;     vload32(vf1, Vb + 32 * VP, lane);
;     SCHED_FENCE();
;     }
;     pvmm32(O, P1, vf1);
; template <int NC>
; __device__ __forceinline__ void attn_shared_unit(LAS char* lds, bf16* qbase, const bf16* Kg, const bf16* Vg, int kvp, int nt, int qpos, int qw, float nslope, float negM0, float lam, const float* subln, int wave_id) {
;     ...
;             if (t + 3 < t_hi) LOADB(t + 3);
	v_mfma_f32_32x32x16_bf16 v[146:161], v[36:39], v[174:177], v[146:161]
	v_mov_b64_e32 v[214:215], v[174:175]
	v_mov_b64_e32 v[176:177], v[172:173]
	v_add_f32_e32 v16, v10, v16
	v_exp_f32_e32 v14, v14
	v_mov_b64_e32 v[174:175], v[170:171]
	v_mov_b64_e32 v[172:173], v[168:169]
	v_add_f32_e32 v16, v11, v16
	v_exp_f32_e32 v15, v15
	v_mov_b64_e32 v[170:171], v[166:167]
	v_mov_b64_e32 v[168:169], v[164:165]
	v_add_f32_e32 v16, v12, v16
	v_mov_b64_e32 v[166:167], v[162:163]
	s_waitcnt vmcnt(0)
	v_mov_b64_e32 v[162:163], v[210:211]
	v_add_f32_e32 v16, v13, v16
	v_mov_b64_e32 v[164:165], v[212:213]
	v_mov_b64_e32 v[212:213], v[204:205]
	v_add_f32_e32 v16, v14, v16
	v_mov_b64_e32 v[210:211], v[202:203]
	v_mov_b64_e32 v[204:205], v[192:193]
	v_add_f32_e32 v16, v15, v16
	v_mov_b64_e32 v[202:203], v[190:191]
	v_cvt_pk_bf16_f32 v190, v8, v9
	v_cvt_pk_bf16_f32 v191, v10, v11
	v_cvt_pk_bf16_f32 v192, v12, v13
	v_cvt_pk_bf16_f32 v193, v14, v15
	v_cvt_pk_bf16_f32 v130, v0, v1
	v_cvt_pk_bf16_f32 v131, v2, v3
	v_cvt_pk_bf16_f32 v132, v4, v5
	v_cvt_pk_bf16_f32 v133, v6, v7
	v_exp_f32_e32 v142, v146
	v_exp_f32_e32 v143, v147
	v_exp_f32_e32 v146, v148
	v_exp_f32_e32 v147, v149
	v_add_f32_e32 v0, v16, v142
	v_exp_f32_e32 v148, v150
	v_add_f32_e32 v0, v143, v0
	v_exp_f32_e32 v149, v151
	v_add_f32_e32 v0, v146, v0
	v_exp_f32_e32 v150, v152
	v_add_f32_e32 v0, v147, v0
	v_exp_f32_e32 v151, v153
	v_add_f32_e32 v0, v148, v0
	v_exp_f32_e32 v153, v154
	s_waitcnt lgkmcnt(11)
	v_mfma_f32_32x32x16_bf16 v[48:63], v[24:27], v[130:133], v[64:79]
	v_add_f32_e32 v0, v149, v0
	v_exp_f32_e32 v154, v155
	v_add_f32_e32 v0, v150, v0
	v_exp_f32_e32 v155, v156
	v_add_f32_e32 v152, v151, v0
	v_exp_f32_e32 v156, v157
	v_exp_f32_e32 v157, v159
	s_waitcnt lgkmcnt(10)
	v_mfma_f32_32x32x16_bf16 v[32:47], v[236:239], v[130:133], v[80:95]
	s_waitcnt lgkmcnt(9)
	v_mfma_f32_32x32x16_bf16 v[16:31], v[240:243], v[130:133], v[96:111]
	s_waitcnt lgkmcnt(8)
	v_mfma_f32_32x32x16_bf16 v[0:15], v[244:247], v[130:133], v[112:127]
	v_add_f32_e32 v130, v153, v152
	v_exp_f32_e32 v152, v158
	v_add_f32_e32 v130, v154, v130
	v_add_f32_e32 v130, v155, v130
	v_add_f32_e32 v130, v156, v130
	v_add_f32_e32 v130, v152, v130
	v_add_f32_e32 v130, v157, v130
	s_waitcnt lgkmcnt(3)
	v_mfma_f32_32x32x16_bf16 v[48:63], v[134:137], v[190:193], v[48:63]
	v_cvt_pk_bf16_f32 v131, v146, v147
	v_cvt_pk_bf16_f32 v132, v148, v149
	v_cvt_pk_bf16_f32 v133, v150, v151
	v_cvt_pk_bf16_f32 v134, v153, v154
	v_cvt_pk_bf16_f32 v135, v155, v156
	v_cvt_pk_bf16_f32 v136, v152, v157
	v_exp_f32_e32 v137, v160
	s_waitcnt lgkmcnt(2)
	v_mfma_f32_32x32x16_bf16 v[32:47], v[138:141], v[190:193], v[32:47]
	ds_read_b64_tr_b16 v[138:139], v221
	ds_read_b64_tr_b16 v[146:147], v221 offset:64
	ds_read_b64_tr_b16 v[150:151], v221 offset:128
	ds_read_b64_tr_b16 v[154:155], v221 offset:192
	ds_read_b64_tr_b16 v[140:141], v221 offset:2560
	ds_read_b64_tr_b16 v[148:149], v221 offset:2624
	ds_read_b64_tr_b16 v[152:153], v221 offset:2688
	ds_read_b64_tr_b16 v[156:157], v221 offset:2752
	v_exp_f32_e32 v158, v161
	v_add_f32_e32 v130, v137, v130
	v_add_f32_e32 v229, v158, v130
	v_cvt_pk_bf16_f32 v130, v142, v143
	s_waitcnt lgkmcnt(9)
	v_mfma_f32_32x32x16_bf16 v[16:31], v[248:251], v[190:193], v[16:31]
	v_fma_f32 v142, v218, v234, v254
	v_cvt_pk_bf16_f32 v137, v137, v158
	s_waitcnt lgkmcnt(8)
	v_mfma_f32_32x32x16_bf16 v[0:15], v[178:181], v[190:193], v[0:15]
	v_mov_b64_e32 v[190:191], v[202:203]
	v_mov_b64_e32 v[192:193], v[204:205]
	v_mov_b64_e32 v[202:203], v[210:211]
	v_mov_b64_e32 v[204:205], v[212:213]
	v_mov_b64_e32 v[212:213], v[164:165]
	v_mov_b64_e32 v[178:179], v[194:195]
	v_mov_b64_e32 v[210:211], v[162:163]
	v_mov_b64_e32 v[162:163], v[166:167]
	v_mov_b64_e32 v[180:181], v[196:197]
	v_mov_b64_e32 v[196:197], v[184:185]
	v_mov_b64_e32 v[164:165], v[168:169]
	v_mov_b64_e32 v[166:167], v[170:171]
	v_mov_b64_e32 v[194:195], v[182:183]
	v_mov_b64_e32 v[182:183], v[186:187]
	v_mov_b64_e32 v[168:169], v[172:173]
	v_mov_b64_e32 v[170:171], v[174:175]
	v_mov_b64_e32 v[184:185], v[188:189]
	v_mov_b64_e32 v[186:187], v[198:199]
	v_mov_b64_e32 v[172:173], v[176:177]
	v_mov_b64_e32 v[174:175], v[214:215]
	v_mov_b64_e32 v[188:189], v[200:201]
	v_mov_b64_e32 v[198:199], v[206:207]
	v_mov_b64_e32 v[176:177], v[216:217]
	v_mov_b64_e32 v[216:217], v[222:223]
	v_mov_b64_e32 v[200:201], v[208:209]
	v_mov_b64_e32 v[208:209], v[230:231]
	s_cmp_ge_i32 s88, s57
	s_cbranch_scc1 .Lmy_a_ldb_skip1
	global_load_dwordx4 v[182:185], v[216:217], off offset:-1024
	global_load_dwordx4 v[186:189], v[216:217], off offset:-1040
	global_load_dwordx4 v[198:201], v[216:217], off
	global_load_dwordx4 v[210:213], v[216:217], off offset:-16

; #define LAS __attribute__((address_space(3)))
; __device__ __forceinline__ s16x4 vtr(const LAS char* p) { return __builtin_bit_cast(s16x4, __builtin_amdgcn_ds_read_tr16_b64_v4i16((LAS v4i16_t*)p)); }
; template <int NK>
; __device__ __forceinline__ void qk32(f32x16& S, const LAS char* Kp, const bf16x8* Q, int ks0, int r32, int hi) {
;     const LAS char* kb = Kp + r32 * KP + hi * 16 + ks0 * 32;
; #pragma unroll
;     for (int ks = 0; ks < NK; ++ks) { const bf16x8 kf = *(const LAS bf16x8*)(kb + ks * 32); S = __builtin_amdgcn_mfma_f32_32x32x16_bf16(kf, Q[ks0 + ks], S, 0, 0, 0); }
; }
; __device__ __forceinline__ void pv32(f32x16 (&O)[4], const bf16x8 (&P)[2], const LAS char* Vp, int lane) {
;     const int i = lane & 15, q = i >> 2, p = i & 3, dsel = (lane >> 4) & 1, h = lane >> 5;
;     const LAS char* vb = Vp + (4 * h + q) * VP + (16 * dsel + 4 * p) * 2;
; #pragma unroll
;     for (int s = 0; s < 2; ++s)
; #pragma unroll
;         for (int db = 0; db < 4; ++db) {
;             const s16x4 lo = vtr(vb + (16 * s) * VP + db * 64), hi4 = vtr(vb + (16 * s + 8) * VP + db * 64);
;             const bf16x8 a = (bf16x8){lo[0], lo[1], lo[2], lo[3], hi4[0], hi4[1], hi4[2], hi4[3]};
;             O[db] = __builtin_amdgcn_mfma_f32_32x32x16_bf16(a, P[s], O[db], 0, 0, 0);
;         }
; template <bool SEG2>
; __device__ __forceinline__ void attn_b_block_unit(LAS char* lds, bf16* R, float* LB, int b, int g, int j, int res0, int q0, int dil, float nslope, float negM0, int wave_id) {
;     ...
;         for (int hh = 0; hh < (SEG2 ? 1 : 2); ++hh) {
;             const int row0 = SEG2 ? 32 * (wave_id >> 2) : 32 * hh, kbase = SEG2 ? kb : kb + 32 * hh;
;             if (kbase + 31 >= qs - 64 && kbase <= qs + 95) {
;                 f32x16 S;
; #pragma unroll
;                 for (int r = 0; r < 16; ++r) S[r] = negM0;
;                 qk32<8>(S, Kb + row0 * KP, Q, 0, r32, hi);
;                 bf16x8 P[2];
;                 soft32<2>(S, P, l, qf - (float)kbase, nslope);
;                 pv32(O, P, Vb + row0 * VP, lane);
;             }
.LBB0_326:
	s_add_i32 s10, s5, 31
	s_cmp_lt_i32 s10, s88
	s_cselect_b64 s[26:27], -1, 0
	s_cmp_gt_u32 s5, s89
	s_cselect_b64 s[68:69], -1, 0
	s_or_b64 s[26:27], s[26:27], s[68:69]
	s_and_b64 vcc, exec, s[26:27]
	s_cbranch_vccnz .LBB0_328
	s_bitcmp1_b32 s7, 0
	s_cselect_b32 s10, 0x9400, 0
	s_add_i32 s10, s10, 0
	s_mul_i32 s26, s39, 0x2200
	s_add_i32 s26, s10, s26
	v_add3_u32 v170, s26, v151, v16
	ds_read_b128 v[186:189], v170
	ds_read_b128 v[190:193], v170 offset:32
	ds_read_b128 v[194:197], v170 offset:64
	ds_read_b128 v[198:201], v170 offset:96
	ds_read_b128 v[202:205], v170 offset:128
	ds_read_b128 v[206:209], v170 offset:160
	ds_read_b128 v[210:213], v170 offset:192
	ds_read_b128 v[214:217], v170 offset:224
	v_cvt_f32_i32_e32 v150, v156
	s_mul_i32 s26, s39, 0x2800
	s_waitcnt lgkmcnt(7)
	v_mfma_f32_32x32x16_bf16 v[82:97], v[186:189], v[106:109], v[0:15]
	v_add_f32_e32 v181, -1.0, v150
	v_add_f32_e64 v168, v150, s50
	v_add_f32_e64 v169, v150, s51
	v_cmp_le_f32_e64 vcc, |v150|, s33
	v_add_f32_e64 v172, v150, s52
	v_add_f32_e64 v173, v150, s53
	v_pk_add_f32 v[174:175], v[150:151], s[46:47] op_sel_hi:[0,1]
	v_pk_add_f32 v[176:177], v[150:151], s[54:55] op_sel_hi:[0,1]
	s_add_i32 s10, s10, s26
	s_waitcnt lgkmcnt(6)
	v_mfma_f32_32x32x16_bf16 v[82:97], v[190:193], v[110:113], v[82:97]
	v_add3_u32 v180, s10, v154, v155
	v_add_f32_e64 v178, v150, s56
	v_add_f32_e64 v179, v150, s57
	s_waitcnt lgkmcnt(5)
	v_mfma_f32_32x32x16_bf16 v[82:97], v[194:197], v[114:117], v[82:97]
	s_waitcnt lgkmcnt(4)
	v_mfma_f32_32x32x16_bf16 v[82:97], v[198:201], v[126:129], v[82:97]
	s_waitcnt lgkmcnt(3)
	v_mfma_f32_32x32x16_bf16 v[82:97], v[202:205], v[130:133], v[82:97]
	s_waitcnt lgkmcnt(2)
	v_mfma_f32_32x32x16_bf16 v[82:97], v[206:209], v[134:137], v[82:97]
	v_add_f32_e64 v170, v150, s44
	v_add_f32_e64 v171, v150, s45
	s_waitcnt lgkmcnt(1)
	v_mfma_f32_32x32x16_bf16 v[82:97], v[210:213], v[138:141], v[82:97]
	ds_read_b64_tr_b16 v[218:219], v180 offset:17408
	ds_read_b64_tr_b16 v[220:221], v180 offset:19968
	ds_read_b64_tr_b16 v[222:223], v180 offset:17472
	ds_read_b64_tr_b16 v[224:225], v180 offset:20032
	ds_read_b64_tr_b16 v[226:227], v180 offset:17536
	ds_read_b64_tr_b16 v[228:229], v180 offset:20096
	ds_read_b64_tr_b16 v[230:231], v180 offset:17600
	ds_read_b64_tr_b16 v[232:233], v180 offset:20160
	ds_read_b64_tr_b16 v[234:235], v180 offset:22528
	ds_read_b64_tr_b16 v[236:237], v180 offset:25088
	ds_read_b64_tr_b16 v[238:239], v180 offset:22592
	ds_read_b64_tr_b16 v[240:241], v180 offset:25152
	ds_read_b64_tr_b16 v[242:243], v180 offset:22656
	ds_read_b64_tr_b16 v[244:245], v180 offset:25216
	ds_read_b64_tr_b16 v[246:247], v180 offset:22720
	ds_read_b64_tr_b16 v[248:249], v180 offset:25280
	s_waitcnt lgkmcnt(0)
	v_mfma_f32_32x32x16_bf16 v[82:97], v[214:217], v[142:145], v[82:97]
	s_nop 11
	v_fma_f32 v82, v147, |v150|, v82
	v_fma_f32 v83, v147, |v181|, v83
	v_exp_f32_e32 v82, v82
	v_fma_f32 v85, v147, |v169|, v85
	v_exp_f32_e32 v83, v83
	v_fma_f32 v84, v147, |v168|, v84
	v_exp_f32_e32 v85, v85
	v_fma_f32 v87, v147, |v171|, v87
	v_exp_f32_e32 v84, v84
	v_fma_f32 v86, v147, |v170|, v86
	v_exp_f32_e32 v87, v87
	v_cndmask_b32_e32 v182, 0, v82, vcc
	v_cmp_le_f32_e64 vcc, |v181|, s33
	v_fma_f32 v89, v147, |v173|, v89
	v_exp_f32_e32 v86, v86
	v_cndmask_b32_e32 v181, 0, v83, vcc
	v_cmp_le_f32_e64 vcc, |v169|, s33
	v_fma_f32 v88, v147, |v172|, v88
	v_exp_f32_e32 v89, v89
	v_cndmask_b32_e32 v169, 0, v85, vcc
	v_cmp_le_f32_e64 vcc, |v168|, s33
	v_fma_f32 v91, v147, |v175|, v91
	v_exp_f32_e32 v88, v88
	v_cndmask_b32_e32 v168, 0, v84, vcc
	v_cmp_le_f32_e64 vcc, |v171|, s33
	v_fma_f32 v90, v147, |v174|, v90
	v_exp_f32_e32 v91, v91
	v_cndmask_b32_e32 v171, 0, v87, vcc
	v_cmp_le_f32_e64 vcc, |v170|, s33
	v_fma_f32 v93, v147, |v177|, v93
	v_exp_f32_e32 v90, v90
	v_cndmask_b32_e32 v170, 0, v86, vcc
	v_cmp_le_f32_e64 vcc, |v173|, s33
	v_fma_f32 v92, v147, |v176|, v92
	v_exp_f32_e32 v93, v93
	v_cndmask_b32_e32 v173, 0, v89, vcc
	v_cmp_le_f32_e64 vcc, |v172|, s33
	v_exp_f32_e32 v92, v92
	v_fma_f32 v95, v147, |v179|, v95
	v_cndmask_b32_e32 v172, 0, v88, vcc
	v_cmp_le_f32_e64 vcc, |v175|, s33
	v_cvt_pk_bf16_f32 v82, v182, v181
	v_cvt_pk_bf16_f32 v83, v168, v169
	v_cndmask_b32_e32 v175, 0, v91, vcc
	v_cmp_le_f32_e64 vcc, |v174|, s33
	v_cvt_pk_bf16_f32 v84, v170, v171
	v_cvt_pk_bf16_f32 v85, v172, v173
	v_cndmask_b32_e32 v174, 0, v90, vcc
	v_cmp_le_f32_e64 vcc, |v177|, s33
	v_exp_f32_e32 v95, v95
	v_fma_f32 v94, v147, |v178|, v94
	v_cndmask_b32_e32 v177, 0, v93, vcc
	v_cmp_le_f32_e64 vcc, |v176|, s33
	s_waitcnt lgkmcnt(14)
	v_mfma_f32_32x32x16_bf16 v[66:81], v[218:221], v[82:85], v[66:81]
	v_exp_f32_e32 v94, v94
	v_cndmask_b32_e32 v176, 0, v92, vcc
	v_cmp_le_f32_e64 vcc, |v179|, s33
	s_nop 1
	v_cndmask_b32_e32 v179, 0, v95, vcc
	s_waitcnt lgkmcnt(12)
	v_mfma_f32_32x32x16_bf16 v[50:65], v[222:225], v[82:85], v[50:65]
	v_add_f32_e64 v86, v150, s58
	v_add_f32_e64 v87, v150, s59
	v_fma_f32 v88, v147, |v87|, v97
	v_exp_f32_e32 v88, v88
	v_fma_f32 v89, v147, |v86|, v96
	v_exp_f32_e32 v89, v89
	v_cmp_le_f32_e64 vcc, |v178|, s33
	s_waitcnt lgkmcnt(10)
	v_mfma_f32_32x32x16_bf16 v[34:49], v[226:229], v[82:85], v[34:49]
	v_cndmask_b32_e32 v178, 0, v94, vcc
	v_cmp_le_f32_e64 vcc, |v87|, s33
	v_cvt_pk_bf16_f32 v87, v176, v177
	s_nop 0
	v_cndmask_b32_e32 v150, 0, v88, vcc
	v_cmp_le_f32_e64 vcc, |v86|, s33
	v_cvt_pk_bf16_f32 v86, v174, v175
	v_cvt_pk_bf16_f32 v88, v178, v179
	v_cndmask_b32_e32 v183, 0, v89, vcc
	s_waitcnt lgkmcnt(8)
	v_mfma_f32_32x32x16_bf16 v[18:33], v[230:233], v[82:85], v[18:33]
	v_cvt_pk_bf16_f32 v89, v183, v150
	s_waitcnt lgkmcnt(6)
	v_mfma_f32_32x32x16_bf16 v[66:81], v[234:237], v[86:89], v[66:81]
	v_add_f32_e32 v90, v157, v182
	v_add_f32_e32 v90, v181, v90
	s_waitcnt lgkmcnt(4)
	v_mfma_f32_32x32x16_bf16 v[50:65], v[238:241], v[86:89], v[50:65]
	v_add_f32_e32 v82, v168, v90
	v_add_f32_e32 v82, v169, v82
	v_add_f32_e32 v82, v170, v82
	v_add_f32_e32 v82, v171, v82
	v_add_f32_e32 v82, v172, v82
	v_add_f32_e32 v82, v173, v82
	v_add_f32_e32 v82, v174, v82
	s_waitcnt lgkmcnt(2)
	v_mfma_f32_32x32x16_bf16 v[34:49], v[242:245], v[86:89], v[34:49]
	v_add_f32_e32 v82, v175, v82
	v_add_f32_e32 v82, v176, v82
	v_add_f32_e32 v82, v177, v82
	v_add_f32_e32 v82, v178, v82
	v_add_f32_e32 v82, v179, v82
	v_add_f32_e32 v82, v183, v82
	v_add_f32_e32 v157, v150, v82
	s_waitcnt lgkmcnt(0)
	v_mfma_f32_32x32x16_bf16 v[18:33], v[246:249], v[86:89], v[18:33]

; #define LAS __attribute__((address_space(3)))
; __device__ __forceinline__ s16x4 vtr(const LAS char* p) { return __builtin_bit_cast(s16x4, __builtin_amdgcn_ds_read_tr16_b64_v4i16((LAS v4i16_t*)p)); }
; template <int NK>
; __device__ __forceinline__ void qk32(f32x16& S, const LAS char* Kp, const bf16x8* Q, int ks0, int r32, int hi) {
;     const LAS char* kb = Kp + r32 * KP + hi * 16 + ks0 * 32;
; #pragma unroll
;     for (int ks = 0; ks < NK; ++ks) { const bf16x8 kf = *(const LAS bf16x8*)(kb + ks * 32); S = __builtin_amdgcn_mfma_f32_32x32x16_bf16(kf, Q[ks0 + ks], S, 0, 0, 0); }
; }
; __device__ __forceinline__ void pv32(f32x16 (&O)[4], const bf16x8 (&P)[2], const LAS char* Vp, int lane) {
;     const int i = lane & 15, q = i >> 2, p = i & 3, dsel = (lane >> 4) & 1, h = lane >> 5;
;     const LAS char* vb = Vp + (4 * h + q) * VP + (16 * dsel + 4 * p) * 2;
; #pragma unroll
;     for (int s = 0; s < 2; ++s)
; #pragma unroll
;         for (int db = 0; db < 4; ++db) {
;             const s16x4 lo = vtr(vb + (16 * s) * VP + db * 64), hi4 = vtr(vb + (16 * s + 8) * VP + db * 64);
;             const bf16x8 a = (bf16x8){lo[0], lo[1], lo[2], lo[3], hi4[0], hi4[1], hi4[2], hi4[3]};
;             O[db] = __builtin_amdgcn_mfma_f32_32x32x16_bf16(a, P[s], O[db], 0, 0, 0);
;         }
; template <bool SEG2>
; __device__ __forceinline__ void attn_b_block_unit(LAS char* lds, bf16* R, float* LB, int b, int g, int j, int res0, int q0, int dil, float nslope, float negM0, int wave_id) {
;     ...
;         for (int hh = 0; hh < (SEG2 ? 1 : 2); ++hh) {
;             const int row0 = SEG2 ? 32 * (wave_id >> 2) : 32 * hh, kbase = SEG2 ? kb : kb + 32 * hh;
;             if (kbase + 31 >= qs - 64 && kbase <= qs + 95) {
;                 f32x16 S;
; #pragma unroll
;                 for (int r = 0; r < 16; ++r) S[r] = negM0;
;                 qk32<8>(S, Kb + row0 * KP, Q, 0, r32, hi);
;                 bf16x8 P[2];
;                 soft32<2>(S, P, l, qf - (float)kbase, nslope);
;                 pv32(O, P, Vb + row0 * VP, lane);
;             }
.LBB0_338:
	s_bitcmp1_b32 s27, 0
	s_cselect_b32 s27, 0x9400, 0
	s_add_i32 s27, s27, 0
	v_add_u32_e32 v16, s27, v170
	v_add_u32_e32 v19, s27, v171
	s_add_i32 s27, s5, 31
	s_cmp_lt_i32 s27, s78
	s_cselect_b64 vcc, -1, 0
	s_cmp_gt_u32 s5, s79
	s_cselect_b64 s[90:91], -1, 0
	s_or_b64 s[90:91], vcc, s[90:91]
	s_and_b64 vcc, exec, s[90:91]
	v_add_u32_e32 v18, v16, v160
	v_add_u32_e32 v16, v19, v172
	s_cbranch_vccnz .LBB0_340
	ds_read_b128 v[186:189], v18
	ds_read_b128 v[190:193], v18 offset:32
	ds_read_b128 v[194:197], v18 offset:64
	ds_read_b128 v[198:201], v18 offset:96
	ds_read_b128 v[202:205], v18 offset:128
	ds_read_b128 v[206:209], v18 offset:160
	ds_read_b128 v[210:213], v18 offset:192
	ds_read_b128 v[214:217], v18 offset:224
	v_cvt_f32_u32_e32 v19, s5
	s_waitcnt lgkmcnt(7)
	v_mfma_f32_32x32x16_bf16 v[96:111], v[186:189], v[112:115], v[0:15]
	ds_read_b64_tr_b16 v[218:219], v16 offset:17408
	ds_read_b64_tr_b16 v[220:221], v16 offset:19968
	v_sub_f32_e32 v174, v169, v19
	v_add_f32_e32 v19, -1.0, v174
	v_add_f32_e64 v178, v174, s46
	v_add_f32_e64 v179, v174, s47
	v_cmp_le_f32_e64 vcc, |v174|, s33
	v_pk_add_f32 v[176:177], v[174:175], s[52:53] op_sel_hi:[0,1]
	v_pk_add_f32 v[180:181], v[174:175], s[54:55] op_sel_hi:[0,1]
	v_pk_add_f32 v[182:183], v[174:175], s[56:57] op_sel_hi:[0,1]
	s_waitcnt lgkmcnt(8)
	v_mfma_f32_32x32x16_bf16 v[96:111], v[190:193], v[116:119], v[96:111]
	ds_read_b64_tr_b16 v[222:223], v16 offset:17472
	ds_read_b64_tr_b16 v[224:225], v16 offset:20032
	s_waitcnt lgkmcnt(9)
	v_mfma_f32_32x32x16_bf16 v[96:111], v[194:197], v[120:123], v[96:111]
	ds_read_b64_tr_b16 v[226:227], v16 offset:17536
	ds_read_b64_tr_b16 v[228:229], v16 offset:20096
	s_waitcnt lgkmcnt(10)
	v_mfma_f32_32x32x16_bf16 v[96:111], v[198:201], v[124:127], v[96:111]
	ds_read_b64_tr_b16 v[230:231], v16 offset:17600
	ds_read_b64_tr_b16 v[232:233], v16 offset:20160
	s_waitcnt lgkmcnt(11)
	v_mfma_f32_32x32x16_bf16 v[96:111], v[202:205], v[128:131], v[96:111]
	ds_read_b64_tr_b16 v[234:235], v16 offset:22528
	ds_read_b64_tr_b16 v[236:237], v16 offset:25088
	s_waitcnt lgkmcnt(12)
	v_mfma_f32_32x32x16_bf16 v[96:111], v[206:209], v[132:135], v[96:111]
	ds_read_b64_tr_b16 v[238:239], v16 offset:22592
	ds_read_b64_tr_b16 v[240:241], v16 offset:25152
	s_waitcnt lgkmcnt(13)
	v_mfma_f32_32x32x16_bf16 v[96:111], v[210:213], v[136:139], v[96:111]
	ds_read_b64_tr_b16 v[242:243], v16 offset:22656
	ds_read_b64_tr_b16 v[244:245], v16 offset:25216
	v_add_f32_e64 v20, v174, s50
	v_add_f32_e64 v21, v174, s51
	v_add_f32_e64 v22, v174, s44
	v_add_f32_e64 v23, v174, s45
	s_waitcnt lgkmcnt(14)
	v_mfma_f32_32x32x16_bf16 v[96:111], v[214:217], v[140:143], v[96:111]
	ds_read_b64_tr_b16 v[246:247], v16 offset:22720
	ds_read_b64_tr_b16 v[248:249], v16 offset:25280
	s_nop 11
	v_fma_f32 v24, v168, |v174|, v96
	v_fma_f32 v25, v168, |v19|, v97
	v_exp_f32_e32 v24, v24
	v_fma_f32 v27, v168, |v21|, v99
	v_exp_f32_e32 v25, v25
	v_fma_f32 v26, v168, |v20|, v98
	v_exp_f32_e32 v27, v27
	v_fma_f32 v97, v168, |v23|, v101
	v_exp_f32_e32 v26, v26
	v_fma_f32 v96, v168, |v22|, v100
	v_fma_f32 v101, v168, |v179|, v105
	v_exp_f32_e32 v97, v97
	v_cndmask_b32_e32 v105, 0, v24, vcc
	v_cmp_le_f32_e64 vcc, |v19|, s33
	v_fma_f32 v99, v168, |v177|, v103
	v_exp_f32_e32 v96, v96
	v_cndmask_b32_e32 v19, 0, v25, vcc
	v_cmp_le_f32_e64 vcc, |v21|, s33
	v_fma_f32 v98, v168, |v176|, v102
	v_fma_f32 v102, v168, |v180|, v106
	v_exp_f32_e32 v99, v99
	v_cndmask_b32_e32 v106, 0, v27, vcc
	v_cmp_le_f32_e64 vcc, |v20|, s33
	v_fma_f32 v103, v168, |v181|, v107
	v_exp_f32_e32 v98, v98
	v_cndmask_b32_e32 v107, 0, v26, vcc
	v_cmp_le_f32_e64 vcc, |v23|, s33
	v_fma_f32 v100, v168, |v178|, v104
	v_fma_f32 v104, v168, |v183|, v109
	v_exp_f32_e32 v101, v101
	v_cndmask_b32_e32 v109, 0, v97, vcc
	v_cmp_le_f32_e64 vcc, |v22|, s33
	v_exp_f32_e32 v100, v100
	v_exp_f32_e32 v103, v103
	v_cndmask_b32_e32 v175, 0, v96, vcc
	v_cmp_le_f32_e64 vcc, |v177|, s33
	v_exp_f32_e32 v102, v102
	v_cvt_pk_bf16_f32 v20, v105, v19
	v_cndmask_b32_e32 v177, 0, v99, vcc
	v_cmp_le_f32_e64 vcc, |v176|, s33
	v_cvt_pk_bf16_f32 v21, v107, v106
	v_cvt_pk_bf16_f32 v22, v175, v109
	v_cndmask_b32_e32 v176, 0, v98, vcc
	v_cmp_le_f32_e64 vcc, |v179|, s33
	v_cvt_pk_bf16_f32 v23, v176, v177
	s_nop 0
	v_cndmask_b32_e32 v179, 0, v101, vcc
	v_cmp_le_f32_e64 vcc, |v178|, s33
	s_waitcnt lgkmcnt(14)
	v_mfma_f32_32x32x16_bf16 v[80:95], v[218:221], v[20:23], v[80:95]
	v_exp_f32_e32 v28, v104
	v_cndmask_b32_e32 v178, 0, v100, vcc
	v_cmp_le_f32_e64 vcc, |v181|, s33
	v_fma_f32 v29, v168, |v182|, v108
	v_exp_f32_e32 v29, v29
	v_cndmask_b32_e32 v181, 0, v103, vcc
	v_cmp_le_f32_e64 vcc, |v180|, s33
	s_nop 1
	v_cndmask_b32_e32 v180, 0, v102, vcc
	s_waitcnt lgkmcnt(12)
	v_mfma_f32_32x32x16_bf16 v[64:79], v[222:225], v[20:23], v[64:79]
	v_add_f32_e64 v24, v174, s58
	v_add_f32_e64 v25, v174, s59
	v_fma_f32 v26, v168, |v25|, v111
	v_cmp_le_f32_e64 vcc, |v183|, s33
	v_exp_f32_e32 v26, v26
	v_fma_f32 v27, v168, |v24|, v110
	v_cndmask_b32_e32 v104, 0, v28, vcc
	v_cmp_le_f32_e64 vcc, |v182|, s33
	v_exp_f32_e32 v27, v27
	s_waitcnt lgkmcnt(10)
	v_mfma_f32_32x32x16_bf16 v[48:63], v[226:229], v[20:23], v[48:63]
	v_cndmask_b32_e32 v108, 0, v29, vcc
	v_cmp_le_f32_e64 vcc, |v25|, s33
	v_cvt_pk_bf16_f32 v25, v180, v181
	s_nop 0
	v_cndmask_b32_e32 v110, 0, v26, vcc
	v_cmp_le_f32_e64 vcc, |v24|, s33
	v_cvt_pk_bf16_f32 v24, v178, v179
	v_cvt_pk_bf16_f32 v26, v108, v104
	v_cndmask_b32_e32 v111, 0, v27, vcc
	v_cvt_pk_bf16_f32 v27, v111, v110
	s_waitcnt lgkmcnt(8)
	v_mfma_f32_32x32x16_bf16 v[32:47], v[230:233], v[20:23], v[32:47]
	s_waitcnt lgkmcnt(6)
	v_mfma_f32_32x32x16_bf16 v[80:95], v[234:237], v[24:27], v[80:95]
	v_add_f32_e32 v28, v173, v105
	v_add_f32_e32 v19, v19, v28
	v_add_f32_e32 v19, v107, v19
	v_add_f32_e32 v19, v106, v19
	v_add_f32_e32 v19, v175, v19
	v_add_f32_e32 v19, v109, v19
	v_add_f32_e32 v19, v176, v19
	v_add_f32_e32 v19, v177, v19
	s_waitcnt lgkmcnt(4)
	v_mfma_f32_32x32x16_bf16 v[64:79], v[238:241], v[24:27], v[64:79]
	v_add_f32_e32 v19, v178, v19
	v_add_f32_e32 v19, v179, v19
	v_add_f32_e32 v19, v180, v19
	v_add_f32_e32 v19, v181, v19
	v_add_f32_e32 v19, v108, v19
	v_add_f32_e32 v19, v104, v19
	v_add_f32_e32 v19, v111, v19
	s_waitcnt lgkmcnt(2)
	v_mfma_f32_32x32x16_bf16 v[48:63], v[242:245], v[24:27], v[48:63]
	v_add_f32_e32 v173, v110, v19
	s_waitcnt lgkmcnt(0)
	v_mfma_f32_32x32x16_bf16 v[32:47], v[246:249], v[24:27], v[32:47]
; #define LAS __attribute__((address_space(3)))
; __device__ __forceinline__ s16x4 vtr(const LAS char* p) { return __builtin_bit_cast(s16x4, __builtin_amdgcn_ds_read_tr16_b64_v4i16((LAS v4i16_t*)p)); }
; template <int NK>
; __device__ __forceinline__ void qk32(f32x16& S, const LAS char* Kp, const bf16x8* Q, int ks0, int r32, int hi) {
;     const LAS char* kb = Kp + r32 * KP + hi * 16 + ks0 * 32;
; #pragma unroll
;     for (int ks = 0; ks < NK; ++ks) { const bf16x8 kf = *(const LAS bf16x8*)(kb + ks * 32); S = __builtin_amdgcn_mfma_f32_32x32x16_bf16(kf, Q[ks0 + ks], S, 0, 0, 0); }
; }
; __device__ __forceinline__ void pv32(f32x16 (&O)[4], const bf16x8 (&P)[2], const LAS char* Vp, int lane) {
;     const int i = lane & 15, q = i >> 2, p = i & 3, dsel = (lane >> 4) & 1, h = lane >> 5;
;     const LAS char* vb = Vp + (4 * h + q) * VP + (16 * dsel + 4 * p) * 2;
; #pragma unroll
;     for (int s = 0; s < 2; ++s)
; #pragma unroll
;         for (int db = 0; db < 4; ++db) {
;             const s16x4 lo = vtr(vb + (16 * s) * VP + db * 64), hi4 = vtr(vb + (16 * s + 8) * VP + db * 64);
;             const bf16x8 a = (bf16x8){lo[0], lo[1], lo[2], lo[3], hi4[0], hi4[1], hi4[2], hi4[3]};
;             O[db] = __builtin_amdgcn_mfma_f32_32x32x16_bf16(a, P[s], O[db], 0, 0, 0);
;         }
; template <bool SEG2>
; __device__ __forceinline__ void attn_b_block_unit(LAS char* lds, bf16* R, float* LB, int b, int g, int j, int res0, int q0, int dil, float nslope, float negM0, int wave_id) {
;     ...
;         for (int hh = 0; hh < (SEG2 ? 1 : 2); ++hh) {
;             const int row0 = SEG2 ? 32 * (wave_id >> 2) : 32 * hh, kbase = SEG2 ? kb : kb + 32 * hh;
;             if (kbase + 31 >= qs - 64 && kbase <= qs + 95) {
;                 f32x16 S;
; #pragma unroll
;                 for (int r = 0; r < 16; ++r) S[r] = negM0;
;                 qk32<8>(S, Kb + row0 * KP, Q, 0, r32, hi);
;                 bf16x8 P[2];
;                 soft32<2>(S, P, l, qf - (float)kbase, nslope);
;                 pv32(O, P, Vb + row0 * VP, lane);
;             }
.LBB0_340:
	s_add_i32 s27, s5, 32
	s_add_i32 s90, s5, 63
	s_cmp_lt_i32 s90, s78
	s_cselect_b64 s[90:91], -1, 0
	s_cmp_gt_u32 s27, s79
	s_cselect_b64 vcc, -1, 0
	s_or_b64 s[90:91], s[90:91], vcc
	s_and_b64 vcc, exec, s[90:91]
	s_cbranch_vccnz .LBB0_342
	ds_read_b128 v[186:189], v18 offset:8704
	ds_read_b128 v[190:193], v18 offset:8736
	ds_read_b128 v[194:197], v18 offset:8768
	ds_read_b128 v[198:201], v18 offset:8800
	ds_read_b128 v[202:205], v18 offset:8832
	ds_read_b128 v[206:209], v18 offset:8864
	ds_read_b128 v[210:213], v18 offset:8896
	ds_read_b128 v[214:217], v18 offset:8928
	v_cvt_f32_u32_e32 v19, s27
	s_waitcnt lgkmcnt(7)
	v_mfma_f32_32x32x16_bf16 v[96:111], v[186:189], v[112:115], v[0:15]
	ds_read_b64_tr_b16 v[218:219], v16 offset:27648
	ds_read_b64_tr_b16 v[220:221], v16 offset:30208
	v_sub_f32_e32 v174, v169, v19
	v_add_f32_e32 v175, -1.0, v174
	v_add_f32_e64 v176, v174, s46
	v_add_f32_e64 v177, v174, s47
	v_cmp_le_f32_e64 vcc, |v174|, s33
	v_pk_add_f32 v[178:179], v[174:175], s[54:55] op_sel_hi:[0,1]
	v_pk_add_f32 v[180:181], v[174:175], s[56:57] op_sel_hi:[0,1]
	s_waitcnt lgkmcnt(8)
	v_mfma_f32_32x32x16_bf16 v[96:111], v[190:193], v[116:119], v[96:111]
	ds_read_b64_tr_b16 v[222:223], v16 offset:27712
	ds_read_b64_tr_b16 v[224:225], v16 offset:30272
	s_waitcnt lgkmcnt(9)
	v_mfma_f32_32x32x16_bf16 v[96:111], v[194:197], v[120:123], v[96:111]
	ds_read_b64_tr_b16 v[226:227], v16 offset:27776
	ds_read_b64_tr_b16 v[228:229], v16 offset:30336
	s_waitcnt lgkmcnt(10)
	v_mfma_f32_32x32x16_bf16 v[96:111], v[198:201], v[124:127], v[96:111]
	ds_read_b64_tr_b16 v[230:231], v16 offset:27840
	ds_read_b64_tr_b16 v[232:233], v16 offset:30400
	s_waitcnt lgkmcnt(11)
	v_mfma_f32_32x32x16_bf16 v[96:111], v[202:205], v[128:131], v[96:111]
	ds_read_b64_tr_b16 v[234:235], v16 offset:32768
	ds_read_b64_tr_b16 v[236:237], v16 offset:35328
	s_waitcnt lgkmcnt(12)
	v_mfma_f32_32x32x16_bf16 v[96:111], v[206:209], v[132:135], v[96:111]
	ds_read_b64_tr_b16 v[238:239], v16 offset:32832
	ds_read_b64_tr_b16 v[240:241], v16 offset:35392
	v_add_f32_e64 v18, v174, s50
	v_add_f32_e64 v19, v174, s51
	s_waitcnt lgkmcnt(13)
	v_mfma_f32_32x32x16_bf16 v[96:111], v[210:213], v[136:139], v[96:111]
	ds_read_b64_tr_b16 v[242:243], v16 offset:32896
	ds_read_b64_tr_b16 v[244:245], v16 offset:35456
	v_add_f32_e64 v20, v174, s44
	v_add_f32_e64 v21, v174, s45
	v_add_f32_e64 v22, v174, s52
	v_add_f32_e64 v23, v174, s53
	s_waitcnt lgkmcnt(14)
	v_mfma_f32_32x32x16_bf16 v[96:111], v[214:217], v[140:143], v[96:111]
	ds_read_b64_tr_b16 v[246:247], v16 offset:32960
	ds_read_b64_tr_b16 v[248:249], v16 offset:35520
	s_nop 11
	v_fma_f32 v24, v168, |v174|, v96
	v_fma_f32 v25, v168, |v175|, v97
	v_exp_f32_e32 v24, v24
	v_fma_f32 v27, v168, |v19|, v99
	v_exp_f32_e32 v25, v25
	v_fma_f32 v26, v168, |v18|, v98
	v_exp_f32_e32 v27, v27
	v_fma_f32 v97, v168, |v21|, v101
	v_exp_f32_e32 v26, v26
	v_fma_f32 v96, v168, |v20|, v100
	v_fma_f32 v101, v168, |v177|, v105
	v_exp_f32_e32 v97, v97
	v_cndmask_b32_e32 v105, 0, v24, vcc
	v_cmp_le_f32_e64 vcc, |v175|, s33
	v_fma_f32 v98, v168, |v22|, v102
	v_fma_f32 v99, v168, |v23|, v103
	v_fma_f32 v102, v168, |v178|, v106
	v_exp_f32_e32 v96, v96
	v_cndmask_b32_e32 v106, 0, v25, vcc
	v_cmp_le_f32_e64 vcc, |v19|, s33
	v_fma_f32 v103, v168, |v179|, v107
	v_exp_f32_e32 v99, v99
	v_cndmask_b32_e32 v107, 0, v27, vcc
	v_cmp_le_f32_e64 vcc, |v18|, s33
	v_fma_f32 v100, v168, |v176|, v104
	v_fma_f32 v104, v168, |v181|, v109
	v_exp_f32_e32 v98, v98
	v_cndmask_b32_e32 v109, 0, v26, vcc
	v_cmp_le_f32_e64 vcc, |v21|, s33
	v_exp_f32_e32 v101, v101
	v_exp_f32_e32 v100, v100
	v_cndmask_b32_e32 v175, 0, v97, vcc
	v_cmp_le_f32_e64 vcc, |v20|, s33
	v_exp_f32_e32 v103, v103
	v_exp_f32_e32 v102, v102
	v_cndmask_b32_e32 v182, 0, v96, vcc
	v_cmp_le_f32_e64 vcc, |v23|, s33
	v_exp_f32_e32 v26, v104
	v_fma_f32 v27, v168, |v180|, v108
	v_cndmask_b32_e32 v183, 0, v99, vcc
	v_cmp_le_f32_e64 vcc, |v22|, s33
	v_exp_f32_e32 v27, v27
	v_cvt_pk_bf16_f32 v18, v105, v106
	v_cndmask_b32_e32 v184, 0, v98, vcc
	v_cmp_le_f32_e64 vcc, |v177|, s33
	v_cvt_pk_bf16_f32 v19, v109, v107
	v_cvt_pk_bf16_f32 v20, v182, v175
	v_cndmask_b32_e32 v177, 0, v101, vcc
	v_cmp_le_f32_e64 vcc, |v176|, s33
	v_cvt_pk_bf16_f32 v21, v184, v183
	s_nop 0
	v_cndmask_b32_e32 v176, 0, v100, vcc
	v_cmp_le_f32_e64 vcc, |v179|, s33
	s_waitcnt lgkmcnt(14)
	v_mfma_f32_32x32x16_bf16 v[80:95], v[218:221], v[18:21], v[80:95]
	v_cndmask_b32_e32 v179, 0, v103, vcc
	v_cmp_le_f32_e64 vcc, |v178|, s33
	s_nop 1
	v_cndmask_b32_e32 v178, 0, v102, vcc
	v_cmp_le_f32_e64 vcc, |v181|, s33
	s_waitcnt lgkmcnt(12)
	v_mfma_f32_32x32x16_bf16 v[64:79], v[222:225], v[18:21], v[64:79]
	v_cndmask_b32_e32 v30, 0, v26, vcc
	v_cmp_le_f32_e64 vcc, |v180|, s33
	v_add_f32_e64 v22, v174, s58
	v_add_f32_e64 v23, v174, s59
	v_fma_f32 v24, v168, |v23|, v111
	v_cndmask_b32_e32 v31, 0, v27, vcc
	v_exp_f32_e32 v24, v24
	s_waitcnt lgkmcnt(10)
	v_mfma_f32_32x32x16_bf16 v[48:63], v[226:229], v[18:21], v[48:63]
	v_fma_f32 v25, v168, |v22|, v110
	v_exp_f32_e32 v25, v25
	v_cmp_le_f32_e64 vcc, |v23|, s33
	v_cvt_pk_bf16_f32 v23, v178, v179
	s_nop 0
	v_cndmask_b32_e32 v104, 0, v24, vcc
	v_cmp_le_f32_e64 vcc, |v22|, s33
	s_waitcnt lgkmcnt(8)
	v_mfma_f32_32x32x16_bf16 v[32:47], v[230:233], v[18:21], v[32:47]
	v_add_f32_e32 v16, v173, v105
	v_add_f32_e32 v16, v106, v16
	v_add_f32_e32 v16, v109, v16
	v_add_f32_e32 v16, v107, v16
	v_add_f32_e32 v16, v182, v16
	v_add_f32_e32 v16, v175, v16
	v_cndmask_b32_e32 v108, 0, v25, vcc
	v_add_f32_e32 v16, v184, v16
	v_cvt_pk_bf16_f32 v22, v176, v177
	v_cvt_pk_bf16_f32 v24, v31, v30
	v_cvt_pk_bf16_f32 v25, v108, v104
	v_add_f32_e32 v16, v183, v16
	v_add_f32_e32 v16, v176, v16
	s_waitcnt lgkmcnt(6)
	v_mfma_f32_32x32x16_bf16 v[80:95], v[234:237], v[22:25], v[80:95]
	v_add_f32_e32 v16, v177, v16
	v_add_f32_e32 v16, v178, v16
	v_add_f32_e32 v16, v179, v16
	v_add_f32_e32 v16, v31, v16
	v_add_f32_e32 v16, v30, v16
	v_add_f32_e32 v16, v108, v16
	v_add_f32_e32 v173, v104, v16
	s_waitcnt lgkmcnt(4)
	v_mfma_f32_32x32x16_bf16 v[64:79], v[238:241], v[22:25], v[64:79]
	s_waitcnt lgkmcnt(2)
	v_mfma_f32_32x32x16_bf16 v[48:63], v[242:245], v[22:25], v[48:63]
	s_waitcnt lgkmcnt(0)
	v_mfma_f32_32x32x16_bf16 v[32:47], v[246:249], v[22:25], v[32:47]

; #define LAS __attribute__((address_space(3)))
; __device__ __forceinline__ s16x4 vtr(const LAS char* p) { return __builtin_bit_cast(s16x4, __builtin_amdgcn_ds_read_tr16_b64_v4i16((LAS v4i16_t*)p)); }
; template <int NK>
; __device__ __forceinline__ void qk32(f32x16& S, const LAS char* Kp, const bf16x8* Q, int ks0, int r32, int hi) {
;     const LAS char* kb = Kp + r32 * KP + hi * 16 + ks0 * 32;
; #pragma unroll
;     for (int ks = 0; ks < NK; ++ks) { const bf16x8 kf = *(const LAS bf16x8*)(kb + ks * 32); S = __builtin_amdgcn_mfma_f32_32x32x16_bf16(kf, Q[ks0 + ks], S, 0, 0, 0); }
; }
; __device__ __forceinline__ void pv32(f32x16 (&O)[4], const bf16x8 (&P)[2], const LAS char* Vp, int lane) {
;     const int i = lane & 15, q = i >> 2, p = i & 3, dsel = (lane >> 4) & 1, h = lane >> 5;
;     const LAS char* vb = Vp + (4 * h + q) * VP + (16 * dsel + 4 * p) * 2;
; #pragma unroll
;     for (int s = 0; s < 2; ++s)
; #pragma unroll
;         for (int db = 0; db < 4; ++db) {
;             const s16x4 lo = vtr(vb + (16 * s) * VP + db * 64), hi4 = vtr(vb + (16 * s + 8) * VP + db * 64);
;             const bf16x8 a = (bf16x8){lo[0], lo[1], lo[2], lo[3], hi4[0], hi4[1], hi4[2], hi4[3]};
;             O[db] = __builtin_amdgcn_mfma_f32_32x32x16_bf16(a, P[s], O[db], 0, 0, 0);
;         }
; template <bool SEG2>
; __device__ __forceinline__ void attn_b_block_unit(LAS char* lds, bf16* R, float* LB, int b, int g, int j, int res0, int q0, int dil, float nslope, float negM0, int wave_id) {
;     ...
;         for (int hh = 0; hh < (SEG2 ? 1 : 2); ++hh) {
;             const int row0 = SEG2 ? 32 * (wave_id >> 2) : 32 * hh, kbase = SEG2 ? kb : kb + 32 * hh;
;             if (kbase + 31 >= qs - 64 && kbase <= qs + 95) {
;                 f32x16 S;
; #pragma unroll
;                 for (int r = 0; r < 16; ++r) S[r] = negM0;
;                 qk32<8>(S, Kb + row0 * KP, Q, 0, r32, hi);
;                 bf16x8 P[2];
;                 soft32<2>(S, P, l, qf - (float)kbase, nslope);
;                 pv32(O, P, Vb + row0 * VP, lane);
;             }
.LBB0_354:
	s_bitcmp1_b32 s4, 0
	s_cselect_b32 s4, 0x9400, 0
	s_add_i32 s4, s4, 0
	v_add_u32_e32 v82, s4, v153
	v_add_u32_e32 v83, s4, v154
	s_add_i32 s4, s7, 31
	s_cmp_lt_i32 s4, s66
	s_cselect_b64 s[4:5], -1, 0
	s_cmp_gt_u32 s7, s67
	s_cselect_b64 s[26:27], -1, 0
	s_or_b64 s[4:5], s[4:5], s[26:27]
	s_and_b64 vcc, exec, s[4:5]
	v_add_u32_e32 v158, v82, v146
	v_add_u32_e32 v157, v83, v155
	s_cbranch_vccnz .LBB0_356
	ds_read_b128 v[186:189], v158
	ds_read_b128 v[190:193], v158 offset:32
	ds_read_b128 v[194:197], v158 offset:64
	ds_read_b128 v[198:201], v158 offset:96
	ds_read_b128 v[202:205], v158 offset:128
	ds_read_b128 v[206:209], v158 offset:160
	ds_read_b128 v[210:213], v158 offset:192
	ds_read_b128 v[214:217], v158 offset:224
	v_cvt_f32_u32_e32 v159, s7
	s_waitcnt lgkmcnt(7)
	v_mfma_f32_32x32x16_bf16 v[82:97], v[186:189], v[98:101], v[0:15]
	ds_read_b64_tr_b16 v[218:219], v157 offset:17408
	ds_read_b64_tr_b16 v[220:221], v157 offset:19968
	s_waitcnt lgkmcnt(8)
	v_mfma_f32_32x32x16_bf16 v[82:97], v[190:193], v[102:105], v[82:97]
	ds_read_b64_tr_b16 v[222:223], v157 offset:17472
	ds_read_b64_tr_b16 v[224:225], v157 offset:20032
	s_waitcnt lgkmcnt(9)
	v_mfma_f32_32x32x16_bf16 v[82:97], v[194:197], v[106:109], v[82:97]
	ds_read_b64_tr_b16 v[226:227], v157 offset:17536
	ds_read_b64_tr_b16 v[228:229], v157 offset:20096
	s_waitcnt lgkmcnt(10)
	v_mfma_f32_32x32x16_bf16 v[82:97], v[198:201], v[110:113], v[82:97]
	ds_read_b64_tr_b16 v[230:231], v157 offset:17600
	ds_read_b64_tr_b16 v[232:233], v157 offset:20160
	s_waitcnt lgkmcnt(11)
	v_mfma_f32_32x32x16_bf16 v[82:97], v[202:205], v[122:125], v[82:97]
	ds_read_b64_tr_b16 v[234:235], v157 offset:22528
	ds_read_b64_tr_b16 v[236:237], v157 offset:25088
	s_waitcnt lgkmcnt(12)
	v_mfma_f32_32x32x16_bf16 v[82:97], v[206:209], v[126:129], v[82:97]
	ds_read_b64_tr_b16 v[238:239], v157 offset:22592
	ds_read_b64_tr_b16 v[240:241], v157 offset:25152
	s_waitcnt lgkmcnt(13)
	v_mfma_f32_32x32x16_bf16 v[82:97], v[210:213], v[130:133], v[82:97]
	ds_read_b64_tr_b16 v[242:243], v157 offset:22656
	ds_read_b64_tr_b16 v[244:245], v157 offset:25216
	s_waitcnt lgkmcnt(14)
	v_mfma_f32_32x32x16_bf16 v[82:97], v[214:217], v[134:137], v[82:97]
	ds_read_b64_tr_b16 v[246:247], v157 offset:22720
	ds_read_b64_tr_b16 v[248:249], v157 offset:25280
	v_sub_f32_e32 v160, v152, v159
	v_cmp_le_f32_e64 vcc, |v160|, s33
	s_nop 9
	v_fma_f32 v82, v150, |v160|, v82
	v_exp_f32_e32 v82, v82
	s_nop 0
	v_cndmask_b32_e32 v159, 0, v82, vcc
	v_add_f32_e32 v82, v156, v159
	v_add_f32_e32 v156, -1.0, v160
	v_fma_f32 v83, v150, |v156|, v83
	v_exp_f32_e32 v83, v83
	v_cmp_le_f32_e64 vcc, |v156|, s33
	s_nop 1
	v_cndmask_b32_e32 v161, 0, v83, vcc
	v_add_f32_e32 v156, v161, v82
	v_pk_add_f32 v[82:83], v[160:161], s[50:51] op_sel_hi:[0,1]
	v_fma_f32 v84, v150, |v82|, v84
	v_exp_f32_e32 v84, v84
	v_fma_f32 v85, v150, |v83|, v85
	v_exp_f32_e32 v85, v85
	v_cmp_le_f32_e64 vcc, |v82|, s33
	v_cmp_le_f32_e64 s[4:5], |v83|, s33
	s_nop 0
	v_cndmask_b32_e32 v84, 0, v84, vcc
	v_cndmask_b32_e64 v85, 0, v85, s[4:5]
	v_add_f32_e32 v82, v84, v156
	v_add_f32_e32 v156, v85, v82
	v_pk_add_f32 v[82:83], v[160:161], s[44:45] op_sel_hi:[0,1]
	v_fma_f32 v86, v150, |v82|, v86
	v_exp_f32_e32 v86, v86
	v_fma_f32 v87, v150, |v83|, v87
	v_exp_f32_e32 v87, v87
	v_cmp_le_f32_e64 vcc, |v82|, s33
	v_cmp_le_f32_e64 s[4:5], |v83|, s33
	s_nop 0
	v_cndmask_b32_e32 v163, 0, v86, vcc
	v_cndmask_b32_e64 v162, 0, v87, s[4:5]
	v_add_f32_e32 v82, v163, v156
	v_add_f32_e32 v86, v162, v82
	v_pk_add_f32 v[82:83], v[160:161], s[52:53] op_sel_hi:[0,1]
	v_fma_f32 v87, v150, |v82|, v88
	v_exp_f32_e32 v87, v87
	v_fma_f32 v88, v150, |v83|, v89
	v_exp_f32_e32 v88, v88
	v_cmp_le_f32_e64 vcc, |v82|, s33
	v_cmp_le_f32_e64 s[4:5], |v83|, s33
	s_nop 0
	v_cndmask_b32_e32 v164, 0, v87, vcc
	v_cndmask_b32_e64 v89, 0, v88, s[4:5]
	v_add_f32_e32 v82, v164, v86
	v_add_f32_e32 v86, v89, v82
	v_pk_add_f32 v[82:83], v[160:161], s[46:47] op_sel_hi:[0,1]
	v_fma_f32 v87, v150, |v82|, v90
	v_exp_f32_e32 v87, v87
	v_fma_f32 v88, v150, |v83|, v91
	v_exp_f32_e32 v88, v88
	v_cmp_le_f32_e64 vcc, |v82|, s33
	v_cmp_le_f32_e64 s[4:5], |v83|, s33
	v_cvt_pk_bf16_f32 v89, v164, v89
	v_cndmask_b32_e32 v91, 0, v87, vcc
	v_cndmask_b32_e64 v90, 0, v88, s[4:5]
	v_add_f32_e32 v82, v91, v86
	v_add_f32_e32 v86, v90, v82
	v_pk_add_f32 v[82:83], v[160:161], s[54:55] op_sel_hi:[0,1]
	v_fma_f32 v87, v150, |v82|, v92
	v_exp_f32_e32 v87, v87
	v_fma_f32 v88, v150, |v83|, v93
	v_exp_f32_e32 v88, v88
	v_cmp_le_f32_e64 vcc, |v82|, s33
	v_cmp_le_f32_e64 s[4:5], |v83|, s33
	s_nop 0
	v_cndmask_b32_e32 v93, 0, v87, vcc
	v_cndmask_b32_e64 v92, 0, v88, s[4:5]
	v_add_f32_e32 v82, v93, v86
	v_add_f32_e32 v86, v92, v82
	v_pk_add_f32 v[82:83], v[160:161], s[56:57] op_sel_hi:[0,1]
	v_fma_f32 v87, v150, |v82|, v94
	v_exp_f32_e32 v87, v87
	v_fma_f32 v88, v150, |v83|, v95
	v_exp_f32_e32 v88, v88
	v_cmp_le_f32_e64 vcc, |v82|, s33
	v_cmp_le_f32_e64 s[4:5], |v83|, s33
	s_nop 0
	v_cndmask_b32_e32 v95, 0, v87, vcc
	v_cndmask_b32_e64 v94, 0, v88, s[4:5]
	v_add_f32_e32 v82, v95, v86
	v_add_f32_e32 v86, v94, v82
	v_pk_add_f32 v[82:83], v[160:161], s[58:59] op_sel_hi:[0,1]
	v_fma_f32 v87, v150, |v82|, v96
	v_exp_f32_e32 v87, v87
	v_fma_f32 v88, v150, |v83|, v97
	v_exp_f32_e32 v88, v88
	v_cmp_le_f32_e64 vcc, |v82|, s33
	v_cmp_le_f32_e64 s[4:5], |v83|, s33
	v_cvt_pk_bf16_f32 v83, v93, v92
	v_cndmask_b32_e32 v97, 0, v87, vcc
	v_cndmask_b32_e64 v96, 0, v88, s[4:5]
	v_add_f32_e32 v82, v97, v86
	v_add_f32_e32 v156, v96, v82
	v_cvt_pk_bf16_f32 v82, v91, v90
	v_cvt_pk_bf16_f32 v86, v159, v161
	v_cvt_pk_bf16_f32 v87, v84, v85
	v_cvt_pk_bf16_f32 v88, v163, v162
	v_cvt_pk_bf16_f32 v84, v95, v94
	v_cvt_pk_bf16_f32 v85, v97, v96
	s_waitcnt lgkmcnt(14)
	v_mfma_f32_32x32x16_bf16 v[66:81], v[218:221], v[86:89], v[66:81]
	s_waitcnt lgkmcnt(12)
	v_mfma_f32_32x32x16_bf16 v[50:65], v[222:225], v[86:89], v[50:65]
	s_waitcnt lgkmcnt(10)
	v_mfma_f32_32x32x16_bf16 v[34:49], v[226:229], v[86:89], v[34:49]
	s_waitcnt lgkmcnt(8)
	v_mfma_f32_32x32x16_bf16 v[18:33], v[230:233], v[86:89], v[18:33]
	s_waitcnt lgkmcnt(6)
	v_mfma_f32_32x32x16_bf16 v[66:81], v[234:237], v[82:85], v[66:81]
	s_waitcnt lgkmcnt(4)
	v_mfma_f32_32x32x16_bf16 v[50:65], v[238:241], v[82:85], v[50:65]
	s_waitcnt lgkmcnt(2)
	v_mfma_f32_32x32x16_bf16 v[34:49], v[242:245], v[82:85], v[34:49]
	s_waitcnt lgkmcnt(0)
	v_mfma_f32_32x32x16_bf16 v[18:33], v[246:249], v[82:85], v[18:33]
; #define LAS __attribute__((address_space(3)))
; __device__ __forceinline__ unsigned cvtpk(float lo, float hi) { f32x2_t v = {lo, hi}; bf16x2_t b = __builtin_convertvector(v, bf16x2_t); return __builtin_bit_cast(unsigned, b); }
; __device__ __forceinline__ s16x4 vtr(const LAS char* p) { return __builtin_bit_cast(s16x4, __builtin_amdgcn_ds_read_tr16_b64_v4i16((LAS v4i16_t*)p)); }
; template <int NK>
; __device__ __forceinline__ void qk32(f32x16& S, const LAS char* Kp, const bf16x8* Q, int ks0, int r32, int hi) {
;     const LAS char* kb = Kp + r32 * KP + hi * 16 + ks0 * 32;
; #pragma unroll
;     for (int ks = 0; ks < NK; ++ks) { const bf16x8 kf = *(const LAS bf16x8*)(kb + ks * 32); S = __builtin_amdgcn_mfma_f32_32x32x16_bf16(kf, Q[ks0 + ks], S, 0, 0, 0); }
; }
; __device__ __forceinline__ void pv32(f32x16 (&O)[4], const bf16x8 (&P)[2], const LAS char* Vp, int lane) {
;     const int i = lane & 15, q = i >> 2, p = i & 3, dsel = (lane >> 4) & 1, h = lane >> 5;
;     const LAS char* vb = Vp + (4 * h + q) * VP + (16 * dsel + 4 * p) * 2;
; #pragma unroll
;     for (int s = 0; s < 2; ++s)
; #pragma unroll
;         for (int db = 0; db < 4; ++db) {
;             const s16x4 lo = vtr(vb + (16 * s) * VP + db * 64), hi4 = vtr(vb + (16 * s + 8) * VP + db * 64);
;             const bf16x8 a = (bf16x8){lo[0], lo[1], lo[2], lo[3], hi4[0], hi4[1], hi4[2], hi4[3]};
;             O[db] = __builtin_amdgcn_mfma_f32_32x32x16_bf16(a, P[s], O[db], 0, 0, 0);
;         }
; }
; template <int MODE>
; __device__ __forceinline__ void soft32(const f32x16& S, bf16x8 (&P)[2], float& l, float dbase, float nslope) {
;     float p[16];
; #pragma unroll
;     for (int r = 0; r < 16; ++r) {
;         float s = S[r];
;         if (MODE >= 1) { const float a = fabsf(dbase - (float)((r & 3) + 8 * (r >> 2))); s = fmaf(nslope, a, s); float e = __builtin_amdgcn_exp2f(s); if (MODE == 2) e = (a <= 64.f) ? e : 0.f; p[r] = e; }
;         else p[r] = __builtin_amdgcn_exp2f(s);
;         l += p[r];
;     }
; #pragma unroll
;     for (int s = 0; s < 2; ++s) { u32x4 w; w.x = cvtpk(p[8 * s + 0], p[8 * s + 1]); w.y = cvtpk(p[8 * s + 2], p[8 * s + 3]); w.z = cvtpk(p[8 * s + 4], p[8 * s + 5]); w.w = cvtpk(p[8 * s + 6], p[8 * s + 7]); P[s] = __builtin_bit_cast(bf16x8, w); }
; }
.LBB0_356:
	s_add_i32 s4, s7, 32
	s_add_i32 s5, s7, 63
	s_cmp_lt_i32 s5, s66
	s_cselect_b64 s[26:27], -1, 0
	s_cmp_gt_u32 s4, s67
	s_cselect_b64 s[78:79], -1, 0
	s_or_b64 s[26:27], s[26:27], s[78:79]
	s_and_b64 vcc, exec, s[26:27]
	s_cbranch_vccnz .LBB0_358
	ds_read_b128 v[186:189], v158 offset:8704
	ds_read_b128 v[190:193], v158 offset:8736
	ds_read_b128 v[194:197], v158 offset:8768
	ds_read_b128 v[198:201], v158 offset:8800
	ds_read_b128 v[202:205], v158 offset:8832
	ds_read_b128 v[206:209], v158 offset:8864
	ds_read_b128 v[210:213], v158 offset:8896
	ds_read_b128 v[214:217], v158 offset:8928
	s_waitcnt lgkmcnt(7)
	v_mfma_f32_32x32x16_bf16 v[82:97], v[186:189], v[98:101], v[0:15]
	ds_read_b64_tr_b16 v[218:219], v157 offset:27648
	ds_read_b64_tr_b16 v[220:221], v157 offset:30208
	s_waitcnt lgkmcnt(8)
	v_mfma_f32_32x32x16_bf16 v[82:97], v[190:193], v[102:105], v[82:97]
	ds_read_b64_tr_b16 v[222:223], v157 offset:27712
	ds_read_b64_tr_b16 v[224:225], v157 offset:30272
	s_waitcnt lgkmcnt(9)
	v_mfma_f32_32x32x16_bf16 v[82:97], v[194:197], v[106:109], v[82:97]
	ds_read_b64_tr_b16 v[226:227], v157 offset:27776
	ds_read_b64_tr_b16 v[228:229], v157 offset:30336
	s_waitcnt lgkmcnt(10)
	v_mfma_f32_32x32x16_bf16 v[82:97], v[198:201], v[110:113], v[82:97]
	ds_read_b64_tr_b16 v[230:231], v157 offset:27840
	ds_read_b64_tr_b16 v[232:233], v157 offset:30400
	s_waitcnt lgkmcnt(11)
	v_mfma_f32_32x32x16_bf16 v[82:97], v[202:205], v[122:125], v[82:97]
	ds_read_b64_tr_b16 v[234:235], v157 offset:32768
	ds_read_b64_tr_b16 v[236:237], v157 offset:35328
	s_waitcnt lgkmcnt(12)
	v_mfma_f32_32x32x16_bf16 v[82:97], v[206:209], v[126:129], v[82:97]
	ds_read_b64_tr_b16 v[238:239], v157 offset:32832
	ds_read_b64_tr_b16 v[240:241], v157 offset:35392
	s_waitcnt lgkmcnt(13)
	v_mfma_f32_32x32x16_bf16 v[82:97], v[210:213], v[130:133], v[82:97]
	ds_read_b64_tr_b16 v[242:243], v157 offset:32896
	ds_read_b64_tr_b16 v[244:245], v157 offset:35456
	s_waitcnt lgkmcnt(14)
	v_mfma_f32_32x32x16_bf16 v[82:97], v[214:217], v[134:137], v[82:97]
	ds_read_b64_tr_b16 v[246:247], v157 offset:32960
	ds_read_b64_tr_b16 v[248:249], v157 offset:35520
	v_cvt_f32_u32_e32 v158, s4
	v_sub_f32_e32 v158, v152, v158
	v_cmp_le_f32_e64 vcc, |v158|, s33
	s_nop 8
	v_fma_f32 v82, v150, |v158|, v82
	v_exp_f32_e32 v82, v82
	s_nop 0
	v_cndmask_b32_e32 v159, 0, v82, vcc
	v_add_f32_e32 v82, v156, v159
	v_add_f32_e32 v156, -1.0, v158
	v_fma_f32 v83, v150, |v156|, v83
	v_exp_f32_e32 v83, v83
	v_cmp_le_f32_e64 vcc, |v156|, s33
	s_nop 1
	v_cndmask_b32_e32 v160, 0, v83, vcc
	v_add_f32_e32 v156, v160, v82
	v_pk_add_f32 v[82:83], v[158:159], s[50:51] op_sel_hi:[0,1]
	v_fma_f32 v84, v150, |v82|, v84
	v_exp_f32_e32 v84, v84
	v_fma_f32 v85, v150, |v83|, v85
	v_exp_f32_e32 v85, v85
	v_cmp_le_f32_e64 vcc, |v82|, s33
	v_cmp_le_f32_e64 s[4:5], |v83|, s33
	s_nop 0
	v_cndmask_b32_e32 v84, 0, v84, vcc
	v_cndmask_b32_e64 v85, 0, v85, s[4:5]
	v_add_f32_e32 v82, v84, v156
	v_add_f32_e32 v156, v85, v82
	v_pk_add_f32 v[82:83], v[158:159], s[44:45] op_sel_hi:[0,1]
	v_fma_f32 v86, v150, |v82|, v86
	v_exp_f32_e32 v86, v86
	v_fma_f32 v87, v150, |v83|, v87
	v_exp_f32_e32 v87, v87
	v_cmp_le_f32_e64 vcc, |v82|, s33
	v_cmp_le_f32_e64 s[4:5], |v83|, s33
	s_nop 0
	v_cndmask_b32_e32 v162, 0, v86, vcc
	v_cndmask_b32_e64 v161, 0, v87, s[4:5]
	v_add_f32_e32 v82, v162, v156
	v_add_f32_e32 v86, v161, v82
	v_pk_add_f32 v[82:83], v[158:159], s[52:53] op_sel_hi:[0,1]
	v_fma_f32 v87, v150, |v82|, v88
	v_exp_f32_e32 v87, v87
	v_fma_f32 v88, v150, |v83|, v89
	v_exp_f32_e32 v88, v88
	v_cmp_le_f32_e64 vcc, |v82|, s33
	v_cmp_le_f32_e64 s[4:5], |v83|, s33
	s_nop 0
	v_cndmask_b32_e32 v163, 0, v87, vcc
	v_cndmask_b32_e64 v89, 0, v88, s[4:5]
	v_add_f32_e32 v82, v163, v86
	v_add_f32_e32 v86, v89, v82
	v_pk_add_f32 v[82:83], v[158:159], s[46:47] op_sel_hi:[0,1]
	v_fma_f32 v87, v150, |v82|, v90
	v_exp_f32_e32 v87, v87
	v_fma_f32 v88, v150, |v83|, v91
	v_exp_f32_e32 v88, v88
	v_cmp_le_f32_e64 vcc, |v82|, s33
	v_cmp_le_f32_e64 s[4:5], |v83|, s33
	v_cvt_pk_bf16_f32 v89, v163, v89
	v_cndmask_b32_e32 v91, 0, v87, vcc
	v_cndmask_b32_e64 v90, 0, v88, s[4:5]
	v_add_f32_e32 v82, v91, v86
	v_add_f32_e32 v86, v90, v82
	v_pk_add_f32 v[82:83], v[158:159], s[54:55] op_sel_hi:[0,1]
	v_fma_f32 v87, v150, |v82|, v92
	v_exp_f32_e32 v87, v87
	v_fma_f32 v88, v150, |v83|, v93
	v_exp_f32_e32 v88, v88
	v_cmp_le_f32_e64 vcc, |v82|, s33
	v_cmp_le_f32_e64 s[4:5], |v83|, s33
	s_nop 0
	v_cndmask_b32_e32 v93, 0, v87, vcc
	v_cndmask_b32_e64 v92, 0, v88, s[4:5]
	v_add_f32_e32 v82, v93, v86
	v_add_f32_e32 v86, v92, v82
	v_pk_add_f32 v[82:83], v[158:159], s[56:57] op_sel_hi:[0,1]
	v_fma_f32 v87, v150, |v82|, v94
	v_exp_f32_e32 v87, v87
	v_fma_f32 v88, v150, |v83|, v95
	v_exp_f32_e32 v88, v88
	v_cmp_le_f32_e64 vcc, |v82|, s33
	v_cmp_le_f32_e64 s[4:5], |v83|, s33
	s_nop 0
	v_cndmask_b32_e32 v95, 0, v87, vcc
	v_cndmask_b32_e64 v94, 0, v88, s[4:5]
	v_add_f32_e32 v82, v95, v86
	v_add_f32_e32 v86, v94, v82
	v_pk_add_f32 v[82:83], v[158:159], s[58:59] op_sel_hi:[0,1]
	v_fma_f32 v87, v150, |v82|, v96
	v_exp_f32_e32 v87, v87
	v_fma_f32 v88, v150, |v83|, v97
	v_exp_f32_e32 v88, v88
	v_cmp_le_f32_e64 vcc, |v82|, s33
	v_cmp_le_f32_e64 s[4:5], |v83|, s33
	v_cvt_pk_bf16_f32 v83, v93, v92
	v_cndmask_b32_e32 v97, 0, v87, vcc
	v_cndmask_b32_e64 v96, 0, v88, s[4:5]
	v_add_f32_e32 v82, v97, v86
	v_add_f32_e32 v156, v96, v82
	v_cvt_pk_bf16_f32 v82, v91, v90
	v_cvt_pk_bf16_f32 v86, v159, v160
	v_cvt_pk_bf16_f32 v87, v84, v85
	v_cvt_pk_bf16_f32 v88, v162, v161
	v_cvt_pk_bf16_f32 v84, v95, v94
	v_cvt_pk_bf16_f32 v85, v97, v96
	s_waitcnt lgkmcnt(14)
	v_mfma_f32_32x32x16_bf16 v[66:81], v[218:221], v[86:89], v[66:81]
	s_waitcnt lgkmcnt(12)
	v_mfma_f32_32x32x16_bf16 v[50:65], v[222:225], v[86:89], v[50:65]
	s_waitcnt lgkmcnt(10)
	v_mfma_f32_32x32x16_bf16 v[34:49], v[226:229], v[86:89], v[34:49]
	s_waitcnt lgkmcnt(8)
	v_mfma_f32_32x32x16_bf16 v[18:33], v[230:233], v[86:89], v[18:33]
	s_waitcnt lgkmcnt(6)
	v_mfma_f32_32x32x16_bf16 v[66:81], v[234:237], v[82:85], v[66:81]
	s_waitcnt lgkmcnt(4)
	v_mfma_f32_32x32x16_bf16 v[50:65], v[238:241], v[82:85], v[50:65]
	s_waitcnt lgkmcnt(2)
	v_mfma_f32_32x32x16_bf16 v[34:49], v[242:245], v[82:85], v[34:49]
	s_waitcnt lgkmcnt(0)
	v_mfma_f32_32x32x16_bf16 v[18:33], v[246:249], v[82:85], v[18:33]

; #define PG8_STAGE(bufoff, gbase, voff) do { _Pragma("unroll") for (int _i = 0; _i < 2; ++_i) \
;         __builtin_amdgcn_global_load_lds((const unsigned*)((const char*)(gbase) + (voff)[_i]), (PG8_LAS unsigned*)(lds + (bufoff) + ldsw + _i * 8192), 16, 0, 0); } while (0)
; #define PG8_BAR __builtin_amdgcn_s_barrier()
; template <class Epi, class Sched, bool ALIGN_EPI = false, bool SP2 = false>
; __device__ __forceinline__ void gemm_phase(PG8_LAS unsigned char* lds, const Gemm g, const Sched& S, const Epi& E, int wave_id) {
;     ...
;     const int wid = __builtin_amdgcn_readfirstlane(tid >> 6), lane = tid & 63, wr = wid >> 2, wc = wid & 3, fr = lane & 15, fq = lane >> 4;
;     const int K = g.K, nt = K / BK;
;     unsigned voffA[2], voffB[2];
; #pragma unroll
;     for (int i = 0; i < 2; ++i) { int R, C; stage_rc(tid * 16 + i * 8192, R, C); const int Rb = Epi::PERM ? ((R & ~31) + perm32(R & 31)) : R;
;         voffA[i] = (unsigned)(R * g.lda + C) * 2u; voffB[i] = (unsigned)(Rb * K + C) * 2u; }
;     ...
;     const char* cA = (const char*)(cur.src == 0 ? g.A : (cur.src == 1 ? g.A2 : g.A3)) + (size_t)cur.pm * tstepA; const char* cB = (const char*)(cur.src == 0 ? g.Bt : (cur.src == 1 ? g.Bt2 : g.Bt3)) + (size_t)cur.pn * tstepB;
;     S.a_ready(cur);
;     if constexpr (SP2) {
;         PG8_STAGE(PG8_SB(0, 0), cB, voffB); PG8_STAGE(PG8_SB(0, 1), cB + hstepB, voffB); PG8_STAGE(PG8_SA(0, 0), cA, voffA); PG8_STAGE(PG8_SA(0, 1), cA + hstepA, voffA);
;         if (wr == 1) PG8_BAR;
.LBB0_510:
	s_and_b64 vcc, exec, s[10:11]
	s_cbranch_vccnz .LBB0_560
	v_ashrrev_i32_e32 v2, 31, v0
	v_lshrrev_b32_e32 v2, 26, v2
	v_lshlrev_b32_e32 v1, 4, v0
	v_add_u32_e32 v2, v0, v2
	v_bfe_i32 v0, v0, 27, 1
	v_lshrrev_b32_e32 v0, 22, v0
	v_add_u32_e32 v0, v1, v0
	v_and_b32_e32 v0, 0xfffffc00, v0
	v_sub_u32_e32 v0, v1, v0
	v_ashrrev_i32_e32 v9, 6, v2
	v_lshrrev_b32_e32 v2, 4, v0
	v_bitop3_b32 v0, v2, v0, 32 bitop3:0x6c
	v_ashrrev_i32_e32 v3, 31, v0
	v_lshrrev_b32_e32 v3, 26, v3
	v_add_u32_e32 v3, v0, v3
	v_lshlrev_b32_e32 v2, 3, v9
	v_ashrrev_i32_e32 v10, 6, v3
	v_and_b32_e32 v3, 0xc0, v3
	v_and_b32_e32 v2, -16, v2
	v_sub_u32_e32 v0, v0, v3
	v_mov_b32_e32 v3, 1
	v_add_u32_e32 v2, v10, v2
	v_lshlrev_b32_e32 v4, 5, v9
	v_ashrrev_i16_sdwa v0, v3, sext(v0) dst_sel:DWORD dst_unused:UNUSED_PAD src0_sel:DWORD src1_sel:BYTE_0
	v_and_b32_e32 v11, 32, v4
	v_bfe_i32 v12, v0, 0, 16
	v_lshlrev_b32_e32 v4, 1, v2
	v_lshrrev_b32_e32 v5, 2, v2
	v_and_b32_e32 v6, 3, v10
	s_mov_b32 s5, 0x3fffe0
	s_movk_i32 s30, 0x1a00
	v_add_u32_e32 v0, v11, v12
	v_and_b32_e32 v4, 24, v4
	v_and_b32_e32 v5, 4, v5
	v_and_or_b32 v6, v2, s5, v6
	v_mul_lo_u32 v2, v2, s30
	v_or3_b32 v4, v6, v5, v4
	s_waitcnt vmcnt(10)
	v_add_lshl_u32 v128, v0, v2, 1
	v_lshlrev_b32_e32 v0, 1, v0
	s_waitcnt vmcnt(9)
	v_lshl_add_u32 v130, v4, 10, v0
	v_add_u32_e32 v0, 0x2000, v1
	v_ashrrev_i32_e32 v1, 31, v0
	v_lshrrev_b32_e32 v1, 22, v1
	v_add_u32_e32 v1, v0, v1
	v_ashrrev_i32_e32 v13, 10, v1
	v_mul_i32_i24_e32 v1, 0x400, v13
	v_sub_u32_e32 v0, v0, v1
	v_lshrrev_b32_e32 v1, 4, v0
	v_bitop3_b32 v0, v1, v0, 32 bitop3:0x6c
	v_ashrrev_i32_e32 v2, 31, v0
	v_lshrrev_b32_e32 v2, 26, v2
	v_lshlrev_b32_e32 v1, 3, v13
	v_add_u32_e32 v2, v0, v2
	v_and_b32_e32 v1, -16, v1
	v_ashrrev_i32_e32 v14, 6, v2
	v_lshlrev_b32_e32 v4, 5, v13
	v_add_u32_e32 v1, v14, v1
	v_and_b32_e32 v15, 32, v4
	v_and_b32_e32 v4, 3, v14
	s_ashr_i32 s8, s22, 6
	v_and_b32_e32 v2, 0xc0, v2
	v_and_or_b32 v4, v1, s5, v4
	s_ashr_i32 s5, s4, 31
	v_sub_u32_e32 v0, v0, v2
	s_ashr_i32 s23, s22, 8
	s_lshl_b32 s31, s8, 10
	s_lshl_b64 s[6:7], s[4:5], 18
	v_readlane_b32 s5, v255, 3
	v_ashrrev_i16_sdwa v0, v3, sext(v0) dst_sel:DWORD dst_unused:UNUSED_PAD src0_sel:DWORD src1_sel:BYTE_0
	s_add_u32 s48, s5, s6
	v_readlane_b32 s5, v255, 2
	v_bfe_i32 v16, v0, 0, 16
	v_lshlrev_b32_e32 v2, 1, v1
	v_lshrrev_b32_e32 v3, 2, v1
	s_addc_u32 s49, s5, s7
	s_add_i32 s33, s31, 0
	v_add_u32_e32 v0, v15, v16
	v_and_b32_e32 v2, 24, v2
	v_and_b32_e32 v3, 4, v3
	v_mul_lo_u32 v1, v1, s30
	s_add_i32 m0, s33, 0x10000
	v_or3_b32 v2, v4, v3, v2
	v_add_lshl_u32 v132, v0, v1, 1
	v_lshlrev_b32_e32 v0, 1, v0
	global_load_lds_dwordx4 v130, s[48:49]
	s_add_i32 m0, s33, 0x12000
	s_nop 0
	v_lshl_add_u32 v134, v2, 10, v0
	s_add_u32 s6, s48, 0x20000
	global_load_lds_dwordx4 v134, s[48:49]
	s_addc_u32 s7, s49, 0
	s_add_i32 m0, s33, 0x14000
	s_mul_i32 s26, s74, 0x340000
	global_load_lds_dwordx4 v130, s[6:7]
	s_add_i32 m0, s33, 0x16000
	s_mul_hi_i32 s9, s74, 0x340000
	s_add_u32 s44, s18, s26
	s_addc_u32 s45, s19, s9
	s_add_i32 s54, s33, 0x2000
	global_load_lds_dwordx4 v134, s[6:7]
	s_mov_b32 m0, s33
	s_add_u32 s6, s44, 0x1a0000
	global_load_lds_dwordx4 v128, s[44:45]
	s_mov_b32 m0, s54
	s_addc_u32 s7, s45, 0
	s_add_i32 s55, s33, 0x4000
	global_load_lds_dwordx4 v132, s[44:45]
	s_mov_b32 m0, s55
	s_add_i32 s56, s33, 0x6000
	global_load_lds_dwordx4 v128, s[6:7]
	s_mov_b32 m0, s56
	v_mov_b32_e32 v131, 0
	global_load_lds_dwordx4 v132, s[6:7]
	v_mov_b32_e32 v135, v131
	v_mov_b32_e32 v129, v131
	v_mov_b32_e32 v133, v131
	s_cmp_eq_u32 s23, 1
	s_mov_b32 s46, 0
	v_lshl_add_u64 v[6:7], s[48:49], 0, v[130:131]
	v_lshl_add_u64 v[4:5], s[48:49], 0, v[134:135]
	v_lshl_add_u64 v[0:1], s[44:45], 0, v[128:129]
	s_cselect_b64 s[6:7], -1, 0
	s_cmp_lg_u32 s23, 1
	v_lshl_add_u64 v[2:3], s[44:45], 0, v[132:133]
	s_cbranch_scc1 .LBB0_513
	s_barrier

; __device__ __forceinline__ int tid_fresh(int wave) { return wave * 64 + lane_id_fresh(); }
;     __host__ __device__ bool next(int i, Unit& u) const {
;         const long L = (long)i * G + c; if (L >= nwg) return false;
;         int wgid = (int)L; { const int q = nwg / NXCD, r = nwg % NXCD, xcd = wgid % NXCD, off = wgid / NXCD; wgid = (xcd < r ? xcd * (q + 1) : r * (q + 1) + (xcd - r) * q) + off; }
;         const int nig = WGM * nN, gid = wgid / nig, fm = gid * WGM, gsz = (nM - fm) < WGM ? (nM - fm) : WGM;
;         u.pm = fm + ((wgid % nig) % gsz); u.pn = (wgid % nig) / gsz; u.src = 0; return true;
; template <class Epi, class Sched, bool ALIGN_EPI = false, bool SP2 = false>
; __device__ __forceinline__ void gemm_phase(PG8_LAS unsigned char* lds, const Gemm g, const Sched& S, const Epi& E, int wave_id) {
;     const int tid = tid_fresh(wave_id);
;     const int wid = __builtin_amdgcn_readfirstlane(tid >> 6), lane = tid & 63, wr = wid >> 2, wc = wid & 3, fr = lane & 15, fq = lane >> 4;
;     const int K = g.K, nt = K / BK;
;     unsigned voffA[2], voffB[2];
; #pragma unroll
;     for (int i = 0; i < 2; ++i) { int R, C; stage_rc(tid * 16 + i * 8192, R, C); const int Rb = Epi::PERM ? ((R & ~31) + perm32(R & 31)) : R;
;         voffA[i] = (unsigned)(R * g.lda + C) * 2u; voffB[i] = (unsigned)(Rb * K + C) * 2u; }
;     const size_t kstep = (size_t)(BK * 2);
;     const size_t hstepA = (size_t)HALF * g.lda * 2, hstepB = (size_t)HALF * K * 2;
;     const size_t tstepA = 2 * hstepA, tstepB = 2 * hstepB;
;     const unsigned ldsw = (unsigned)wid * 1024u;
;     const int aoff = lds_byte(wr * 64 + fr, fq * 8), boff = lds_byte(wc * 32 + fr, fq * 8);
;     ...
;     Unit cur, nxt; int ui = 0;
;     if (!S.next(0, cur)) return;
;     f32x4 acc[2][2][4][2];
; #pragma unroll
;     for (int a = 0; a < 2; ++a)
; #pragma unroll
;         for (int b = 0; b < 2; ++b)
; #pragma unroll
;             for (int m = 0; m < 4; ++m)
; #pragma unroll
;                 for (int n = 0; n < 2; ++n) acc[a][b][m][n] = (f32x4){0.f, 0.f, 0.f, 0.f};
;     bf16x8 At[4][2], B0[2][2], B1[2][2];
;     const char* cA = (const char*)(cur.src == 0 ? g.A : (cur.src == 1 ? g.A2 : g.A3)) + (size_t)cur.pm * tstepA; const char* cB = (const char*)(cur.src == 0 ? g.Bt : (cur.src == 1 ? g.Bt2 : g.Bt3)) + (size_t)cur.pn * tstepB;
;     S.a_ready(cur);
;     if constexpr (SP2) {
.LBB0_708:
	s_or_b64 exec, exec, s[4:5]
	s_mov_b32 s4, 0
	s_waitcnt lgkmcnt(0)
	s_barrier
	s_add_u32 s8, s14, 0x2f40800
	v_mbcnt_lo_u32_b32 v0, -1, s4
	v_mbcnt_hi_u32_b32 v10, -1, v0
	s_addc_u32 s9, s15, 0
	v_add_u32_e32 v0, s80, v10
	s_cmpk_gt_i32 s2, 0x57f
	v_readfirstlane_b32 s5, v0
	s_cbranch_scc1 .LBB0_726
	v_lshlrev_b32_e32 v1, 4, v0
	v_add_u32_e32 v2, 0x2000, v1
	v_ashrrev_i32_e32 v3, 31, v2
	v_lshrrev_b32_e32 v3, 22, v3
	v_add_u32_e32 v3, v2, v3
	v_ashrrev_i32_e32 v8, 10, v3
	v_mul_i32_i24_e32 v3, 0x400, v8
	v_sub_u32_e32 v2, v2, v3
	v_lshrrev_b32_e32 v3, 4, v2
	v_bitop3_b32 v2, v3, v2, 32 bitop3:0x6c
	v_ashrrev_i32_e32 v3, 31, v2
	v_lshrrev_b32_e32 v3, 26, v3
	v_add_u32_e32 v3, v2, v3
	v_lshlrev_b32_e32 v4, 3, v8
	v_ashrrev_i32_e32 v9, 6, v3
	v_and_b32_e32 v4, -16, v4
	v_add_u32_e32 v4, v9, v4
	v_and_b32_e32 v5, 3, v9
	s_mov_b32 s4, 0x1fffe0
	v_lshrrev_b32_e32 v6, 2, v4
	v_lshlrev_b32_e32 v7, 1, v4
	v_and_b32_e32 v3, 0xc0, v3
	v_and_or_b32 v5, v4, s4, v5
	v_and_b32_e32 v6, 4, v6
	v_and_b32_e32 v7, 24, v7
	v_sub_u32_e32 v2, v2, v3
	v_mov_b32_e32 v3, 1
	v_or3_b32 v5, v5, v6, v7
	v_lshlrev_b32_e32 v6, 5, v8
	v_ashrrev_i16_sdwa v2, v3, sext(v2) dst_sel:DWORD dst_unused:UNUSED_PAD src0_sel:DWORD src1_sel:BYTE_0
	v_and_b32_e32 v11, 32, v6
	v_bfe_i32 v12, v2, 0, 16
	s_movk_i32 s7, 0x1a00
	v_add_u32_e32 v2, v11, v12
	v_mul_lo_u32 v4, v4, s7
	v_lshlrev_b32_e32 v6, 1, v2
	s_waitcnt vmcnt(9)
	v_add_lshl_u32 v130, v2, v4, 1
	v_bfe_i32 v2, v0, 27, 1
	v_lshrrev_b32_e32 v2, 22, v2
	v_add_u32_e32 v2, v1, v2
	v_and_b32_e32 v2, 0xfffffc00, v2
	v_sub_u32_e32 v1, v1, v2
	v_lshrrev_b32_e32 v2, 4, v1
	v_ashrrev_i32_e32 v4, 31, v0
	v_bitop3_b32 v1, v2, v1, 32 bitop3:0x6c
	v_lshrrev_b32_e32 v4, 26, v4
	v_ashrrev_i32_e32 v2, 31, v1
	v_add_u32_e32 v0, v0, v4
	v_lshrrev_b32_e32 v2, 26, v2
	v_ashrrev_i32_e32 v14, 6, v0
	v_add_u32_e32 v2, v1, v2
	v_lshlrev_b32_e32 v0, 3, v14
	v_ashrrev_i32_e32 v13, 6, v2
	v_and_b32_e32 v0, -16, v0
	v_add_u32_e32 v0, v13, v0
	v_and_b32_e32 v4, 3, v13
	s_ashr_i32 s31, s2, 31
	v_and_or_b32 v4, v0, s4, v4
	s_lshr_b32 s4, s31, 29
	s_add_i32 s4, s2, s4
	s_ashr_i32 s20, s5, 6
	s_ashr_i32 s16, s4, 3
	s_and_b32 s4, s4, -8
	s_ashr_i32 s6, s5, 8
	s_lshl_b32 s30, s20, 10
	s_sub_i32 s4, s2, s4
	s_cmp_lt_i32 s4, 0
	s_movk_i32 s33, 0xb1
	s_cselect_b32 s17, s33, 0xb0
	s_mul_i32 s4, s4, s17
	s_add_i32 s4, s4, s16
	s_mul_hi_i32 s16, s4, 0x2e8ba2e9
	s_lshr_b32 s17, s16, 31
	s_ashr_i32 s16, s16, 5
	s_add_i32 s16, s16, s17
	s_lshl_b32 s17, s16, 3
	s_mulk_i32 s16, 0xb0
	s_sub_i32 s16, s4, s16
	s_sext_i32_i16 s4, s16
	s_bfe_u32 s4, s4, 0x3001c
	s_add_i32 s21, s16, s4
	s_sext_i32_i16 s4, s21
	s_and_b32 s21, s21, 0xfff8
	v_lshl_add_u32 v128, v5, 11, v6
	v_lshrrev_b32_e32 v5, 2, v0
	v_lshlrev_b32_e32 v6, 1, v0
	v_and_b32_e32 v2, 0xc0, v2
	s_sub_i32 s16, s16, s21
	v_and_b32_e32 v5, 4, v5
	v_and_b32_e32 v6, 24, v6
	v_sub_u32_e32 v1, v1, v2
	s_lshr_b32 s4, s4, 3
	s_sext_i32_i16 s16, s16
	v_or3_b32 v4, v4, v5, v6
	v_lshlrev_b32_e32 v5, 5, v14
	v_ashrrev_i16_sdwa v1, v3, sext(v1) dst_sel:DWORD dst_unused:UNUSED_PAD src0_sel:DWORD src1_sel:BYTE_0
	s_add_i32 s60, s17, s16
	s_bfe_i64 s[16:17], s[4:5], 0x100000
	v_and_b32_e32 v15, 32, v5
	v_bfe_i32 v16, v1, 0, 16
	s_lshl_b64 s[16:17], s[16:17], 19
	v_add_u32_e32 v1, v15, v16
	s_add_u32 s44, s34, s16
	v_lshlrev_b32_e32 v2, 1, v1
	s_addc_u32 s45, s35, s17
	s_add_i32 s48, s30, 0
	v_lshl_add_u32 v132, v4, 11, v2
	s_add_i32 m0, s48, 0x10000
	s_mul_i32 s22, s60, 0x340000
	global_load_lds_dwordx4 v132, s[44:45]
	s_add_i32 m0, s48, 0x12000
	s_add_u32 s16, s44, 0x40000
	global_load_lds_dwordx4 v128, s[44:45]
	s_addc_u32 s17, s45, 0
	s_add_i32 m0, s48, 0x14000
	s_mul_hi_i32 s21, s60, 0x340000
	global_load_lds_dwordx4 v132, s[16:17]
	s_add_i32 m0, s48, 0x16000
	s_add_u32 s42, s18, s22
	v_mul_lo_u32 v0, v0, s7
	s_addc_u32 s43, s19, s21
	s_add_i32 s49, s48, 0x2000
	s_nop 0
	v_add_lshl_u32 v134, v1, v0, 1
	global_load_lds_dwordx4 v128, s[16:17]
	s_mov_b32 m0, s48
	s_add_u32 s16, s42, 0x1a0000
	global_load_lds_dwordx4 v134, s[42:43]
	s_mov_b32 m0, s49
	s_addc_u32 s17, s43, 0
	s_add_i32 s50, s48, 0x4000
	global_load_lds_dwordx4 v130, s[42:43]
	s_mov_b32 m0, s50
	s_add_i32 s51, s48, 0x6000
	global_load_lds_dwordx4 v134, s[16:17]
	s_mov_b32 m0, s51
	v_mov_b32_e32 v133, 0
	global_load_lds_dwordx4 v130, s[16:17]
	v_mov_b32_e32 v129, v133
	v_mov_b32_e32 v135, v133
	v_mov_b32_e32 v131, v133
	s_cmp_eq_u32 s6, 1
	v_lshl_add_u64 v[6:7], s[44:45], 0, v[132:133]
	v_lshl_add_u64 v[4:5], s[44:45], 0, v[128:129]
	v_lshl_add_u64 v[0:1], s[42:43], 0, v[134:135]
	s_cselect_b64 s[16:17], -1, 0
	s_cmp_lg_u32 s6, 1
	v_lshl_add_u64 v[2:3], s[42:43], 0, v[130:131]
	s_cbranch_scc1 .LBB0_711
	s_barrier

; __device__ __forceinline__ int tid_fresh(int wave) { return wave * 64 + lane_id_fresh(); }
;     __host__ __device__ bool next(int i, Unit& u) const {
;         const long L = (long)i * G + c; if (L >= nwg) return false;
;         int wgid = (int)L; { const int q = nwg / NXCD, r = nwg % NXCD, xcd = wgid % NXCD, off = wgid / NXCD; wgid = (xcd < r ? xcd * (q + 1) : r * (q + 1) + (xcd - r) * q) + off; }
;         const int nig = WGM * nN, gid = wgid / nig, fm = gid * WGM, gsz = (nM - fm) < WGM ? (nM - fm) : WGM;
;         u.pm = fm + ((wgid % nig) % gsz); u.pn = (wgid % nig) / gsz; u.src = 0; return true;
; template <class Epi, class Sched, bool ALIGN_EPI = false, bool SP2 = false>
; __device__ __forceinline__ void gemm_phase(PG8_LAS unsigned char* lds, const Gemm g, const Sched& S, const Epi& E, int wave_id) {
;     const int tid = tid_fresh(wave_id);
;     const int wid = __builtin_amdgcn_readfirstlane(tid >> 6), lane = tid & 63, wr = wid >> 2, wc = wid & 3, fr = lane & 15, fq = lane >> 4;
;     const int K = g.K, nt = K / BK;
;     unsigned voffA[2], voffB[2];
; #pragma unroll
;     for (int i = 0; i < 2; ++i) { int R, C; stage_rc(tid * 16 + i * 8192, R, C); const int Rb = Epi::PERM ? ((R & ~31) + perm32(R & 31)) : R;
;         voffA[i] = (unsigned)(R * g.lda + C) * 2u; voffB[i] = (unsigned)(Rb * K + C) * 2u; }
;     const size_t kstep = (size_t)(BK * 2);
;     const size_t hstepA = (size_t)HALF * g.lda * 2, hstepB = (size_t)HALF * K * 2;
;     const size_t tstepA = 2 * hstepA, tstepB = 2 * hstepB;
;     const unsigned ldsw = (unsigned)wid * 1024u;
;     const int aoff = lds_byte(wr * 64 + fr, fq * 8), boff = lds_byte(wc * 32 + fr, fq * 8);
;     ...
;     Unit cur, nxt; int ui = 0;
;     if (!S.next(0, cur)) return;
;     f32x4 acc[2][2][4][2];
; #pragma unroll
;     for (int a = 0; a < 2; ++a)
; #pragma unroll
;         for (int b = 0; b < 2; ++b)
; #pragma unroll
;             for (int m = 0; m < 4; ++m)
; #pragma unroll
;                 for (int n = 0; n < 2; ++n) acc[a][b][m][n] = (f32x4){0.f, 0.f, 0.f, 0.f};
;     bf16x8 At[4][2], B0[2][2], B1[2][2];
;     const char* cA = (const char*)(cur.src == 0 ? g.A : (cur.src == 1 ? g.A2 : g.A3)) + (size_t)cur.pm * tstepA; const char* cB = (const char*)(cur.src == 0 ? g.Bt : (cur.src == 1 ? g.Bt2 : g.Bt3)) + (size_t)cur.pn * tstepB;
;     S.a_ready(cur);
;     if constexpr (SP2) {
.LBB0_789:
	v_ashrrev_i32_e32 v2, 31, v0
	v_lshrrev_b32_e32 v2, 26, v2
	v_lshlrev_b32_e32 v1, 4, v0
	v_add_u32_e32 v2, v0, v2
	v_bfe_i32 v0, v0, 27, 1
	v_lshrrev_b32_e32 v0, 22, v0
	v_add_u32_e32 v0, v1, v0
	v_and_b32_e32 v0, 0xfffffc00, v0
	v_sub_u32_e32 v0, v1, v0
	v_ashrrev_i32_e32 v9, 6, v2
	v_lshrrev_b32_e32 v2, 4, v0
	v_bitop3_b32 v0, v2, v0, 32 bitop3:0x6c
	v_ashrrev_i32_e32 v3, 31, v0
	v_lshrrev_b32_e32 v3, 26, v3
	v_lshlrev_b32_e32 v2, 3, v9
	v_add_u32_e32 v3, v0, v3
	v_and_b32_e32 v2, -16, v2
	v_ashrrev_i32_e32 v10, 6, v3
	v_and_b32_e32 v3, 0xc0, v3
	v_add_u32_e32 v2, v10, v2
	v_lshlrev_b32_e32 v4, 5, v9
	v_sub_u32_e32 v0, v0, v3
	v_mov_b32_e32 v3, 1
	v_and_b32_e32 v11, 32, v4
	v_ashrrev_i16_sdwa v0, v3, sext(v0) dst_sel:DWORD dst_unused:UNUSED_PAD src0_sel:DWORD src1_sel:BYTE_0
	v_lshlrev_b32_e32 v4, 1, v2
	v_lshrrev_b32_e32 v5, 2, v2
	v_and_b32_e32 v6, 3, v10
	s_mov_b32 s5, 0xffffe0
	v_bfe_i32 v12, v0, 0, 16
	v_and_b32_e32 v4, 24, v4
	v_and_b32_e32 v5, 4, v5
	v_and_or_b32 v6, v2, s5, v6
	s_movk_i32 s0, 0x1a00
	v_add_u32_e32 v0, v11, v12
	v_or3_b32 v4, v6, v5, v4
	v_mul_lo_u32 v2, v2, s0
	s_waitcnt vmcnt(10)
	v_add_lshl_u32 v128, v0, v2, 1
	v_mul_u32_u24_e32 v2, 0xb00, v4
	s_waitcnt vmcnt(9)
	v_add_lshl_u32 v130, v2, v0, 1
	v_add_u32_e32 v0, 0x2000, v1
	v_ashrrev_i32_e32 v1, 31, v0
	s_add_i32 s10, s10, s11
	v_lshrrev_b32_e32 v1, 22, v1
	s_ashr_i32 s11, s10, 31
	v_add_u32_e32 v1, v0, v1
	s_lshr_b32 s11, s11, 27
	v_ashrrev_i32_e32 v13, 10, v1
	s_add_i32 s11, s10, s11
	v_mul_i32_i24_e32 v1, 0x400, v13
	s_ashr_i32 s14, s11, 5
	s_and_b32 s11, s11, 0xffe0
	v_sub_u32_e32 v0, v0, v1
	s_sub_i32 s10, s10, s11
	v_lshrrev_b32_e32 v1, 4, v0
	s_bfe_i32 s11, s10, 0x80000
	v_bitop3_b32 v0, v1, v0, 32 bitop3:0x6c
	s_bfe_u32 s11, s11, 0x3000c
	v_ashrrev_i32_e32 v2, 31, v0
	s_add_i32 s11, s10, s11
	v_lshrrev_b32_e32 v2, 26, v2
	s_bfe_i32 s15, s11, 0x80000
	s_and_b32 s11, s11, 0xf8
	v_lshlrev_b32_e32 v1, 3, v13
	v_add_u32_e32 v2, v0, v2
	s_sub_i32 s10, s10, s11
	v_and_b32_e32 v1, -16, v1
	v_ashrrev_i32_e32 v14, 6, v2
	v_lshlrev_b32_e32 v4, 5, v13
	s_lshl_b32 s14, s14, 3
	s_sext_i32_i16 s15, s15
	s_sext_i32_i8 s10, s10
	s_ashr_i32 s1, s4, 6
	v_add_u32_e32 v1, v14, v1
	v_and_b32_e32 v15, 32, v4
	v_and_b32_e32 v2, 0xc0, v2
	v_and_b32_e32 v4, 3, v14
	s_add_i32 s54, s14, s10
	s_ashr_i32 s10, s15, 3
	v_sub_u32_e32 v0, v0, v2
	v_and_or_b32 v4, v1, s5, v4
	s_ashr_i32 s5, s4, 8
	s_lshl_b32 s25, s1, 10
	s_lshr_b32 s18, s15, 3
	s_mul_hi_i32 s11, s10, 0x160000
	s_mul_i32 s10, s10, 0x160000
	v_ashrrev_i16_sdwa v0, v3, sext(v0) dst_sel:DWORD dst_unused:UNUSED_PAD src0_sel:DWORD src1_sel:BYTE_0
	v_lshlrev_b32_e32 v2, 1, v1
	v_lshrrev_b32_e32 v3, 2, v1
	s_add_u32 s34, s6, s10
	v_bfe_i32 v16, v0, 0, 16
	v_and_b32_e32 v2, 24, v2
	v_and_b32_e32 v3, 4, v3
	s_addc_u32 s35, s7, s11
	s_add_i32 s33, s25, 0
	v_add_u32_e32 v0, v15, v16
	v_or3_b32 v2, v4, v3, v2
	v_mul_lo_u32 v1, v1, s0
	s_add_i32 m0, s33, 0x10000
	v_add_lshl_u32 v132, v0, v1, 1
	v_mul_u32_u24_e32 v1, 0xb00, v2
	global_load_lds_dwordx4 v130, s[34:35]
	s_add_i32 m0, s33, 0x12000
	s_nop 0
	v_add_lshl_u32 v134, v1, v0, 1
	s_add_u32 s10, s34, 0xb0000
	global_load_lds_dwordx4 v134, s[34:35]
	s_addc_u32 s11, s35, 0
	s_add_i32 m0, s33, 0x14000
	s_mul_i32 s16, s54, 0x340000
	global_load_lds_dwordx4 v130, s[10:11]
	s_add_i32 m0, s33, 0x16000
	s_mul_hi_i32 s14, s54, 0x340000
	s_add_u32 s30, s8, s16
	s_addc_u32 s31, s9, s14
	s_add_i32 s40, s33, 0x2000
	global_load_lds_dwordx4 v134, s[10:11]
	s_mov_b32 m0, s33
	s_add_u32 s10, s30, 0x1a0000
	global_load_lds_dwordx4 v128, s[30:31]
	s_mov_b32 m0, s40
	s_addc_u32 s11, s31, 0
	s_add_i32 s41, s33, 0x4000
	global_load_lds_dwordx4 v132, s[30:31]
	s_mov_b32 m0, s41
	s_add_i32 s42, s33, 0x6000
	global_load_lds_dwordx4 v128, s[10:11]
	s_mov_b32 m0, s42
	v_mov_b32_e32 v131, 0
	global_load_lds_dwordx4 v132, s[10:11]
	v_mov_b32_e32 v135, v131
	v_mov_b32_e32 v129, v131
	v_mov_b32_e32 v133, v131
	s_cmp_eq_u32 s5, 1
	s_mov_b32 s43, 0
	v_lshl_add_u64 v[6:7], s[34:35], 0, v[130:131]
	v_lshl_add_u64 v[4:5], s[34:35], 0, v[134:135]
	s_mov_b64 s[10:11], 0xb0000
	v_lshl_add_u64 v[0:1], s[30:31], 0, v[128:129]
	s_cselect_b64 s[14:15], -1, 0
	s_cmp_lg_u32 s5, 1
	v_lshl_add_u64 v[2:3], s[30:31], 0, v[132:133]
	s_cbranch_scc1 .LBB0_791
	s_barrier

; __global__ void __launch_bounds__(512, 2) fwd_megakernel(Args a) {
	.amdhsa_kernel _Z14fwd_megakernel4Args
		.amdhsa_group_segment_fixed_size 0
		.amdhsa_private_segment_fixed_size 0
		.amdhsa_kernarg_size 472
		.amdhsa_user_sgpr_count 2
		.amdhsa_user_sgpr_dispatch_ptr 0
		.amdhsa_user_sgpr_queue_ptr 0
		.amdhsa_user_sgpr_kernarg_segment_ptr 1
		.amdhsa_user_sgpr_dispatch_id 0
		.amdhsa_user_sgpr_kernarg_preload_length 0
		.amdhsa_user_sgpr_kernarg_preload_offset 0
		.amdhsa_user_sgpr_private_segment_size 0
		.amdhsa_uses_dynamic_stack 0
		.amdhsa_enable_private_segment 0
		.amdhsa_system_sgpr_workgroup_id_x 1
		.amdhsa_system_sgpr_workgroup_id_y 0
		.amdhsa_system_sgpr_workgroup_id_z 0
		.amdhsa_system_sgpr_workgroup_info 0
		.amdhsa_system_vgpr_workitem_id 2
		.amdhsa_next_free_vgpr 256
		.amdhsa_next_free_sgpr 102
		.amdhsa_accum_offset 256
		.amdhsa_reserve_vcc 1
		.amdhsa_float_round_mode_32 0
		.amdhsa_float_round_mode_16_64 0
		.amdhsa_float_denorm_mode_32 3
		.amdhsa_float_denorm_mode_16_64 3
		.amdhsa_dx10_clamp 1
		.amdhsa_ieee_mode 1
		.amdhsa_fp16_overflow 0
		.amdhsa_tg_split 0
		.amdhsa_exception_fp_ieee_invalid_op 0
		.amdhsa_exception_fp_denorm_src 0
		.amdhsa_exception_fp_ieee_div_zero 0
		.amdhsa_exception_fp_ieee_overflow 0
		.amdhsa_exception_fp_ieee_underflow 0
		.amdhsa_exception_fp_ieee_inexact 0
		.amdhsa_exception_int_div_zero 0
	.end_amdhsa_kernel

; __global__ void __launch_bounds__(512, 2) fwd_megakernel(Args a) {
amdhsa.kernels:
  - .agpr_count:     0
    .args:
      - .offset:         0
        .size:           216
        .value_kind:     by_value
      - .offset:         216
        .size:           4
        .value_kind:     hidden_block_count_x
      - .offset:         220
        .size:           4
        .value_kind:     hidden_block_count_y
      - .offset:         224
        .size:           4
        .value_kind:     hidden_block_count_z
      - .offset:         228
        .size:           2
        .value_kind:     hidden_group_size_x
      - .offset:         230
        .size:           2
        .value_kind:     hidden_group_size_y
      - .offset:         232
        .size:           2
        .value_kind:     hidden_group_size_z
      - .offset:         234
        .size:           2
        .value_kind:     hidden_remainder_x
      - .offset:         236
        .size:           2
        .value_kind:     hidden_remainder_y
      - .offset:         238
        .size:           2
        .value_kind:     hidden_remainder_z
      - .offset:         256
        .size:           8
        .value_kind:     hidden_global_offset_x
      - .offset:         264
        .size:           8
        .value_kind:     hidden_global_offset_y
      - .offset:         272
        .size:           8
        .value_kind:     hidden_global_offset_z
      - .offset:         280
        .size:           2
        .value_kind:     hidden_grid_dims
      - .offset:         304
        .size:           8
        .value_kind:     hidden_multigrid_sync_arg
      - .offset:         336
        .size:           4
        .value_kind:     hidden_dynamic_lds_size
    .group_segment_fixed_size: 0
    .kernarg_segment_align: 8
    .kernarg_segment_size: 472
    .language:       OpenCL C
    .language_version:
      - 2
      - 0
    .max_flat_workgroup_size: 512
    .name:           _Z14fwd_megakernel4Args
    .private_segment_fixed_size: 0
    .sgpr_count:     108
    .sgpr_spill_count: 13
    .symbol:         _Z14fwd_megakernel4Args.kd
    .uniform_work_group_size: 1
    .uses_dynamic_stack: false
    .vgpr_count:     256
    .vgpr_spill_count: 0
    .wavefront_size: 64
